# counted waits across the tile boundary: peeled first K-iteration of the up-GEMMs uses vmcnt(14)/vmcnt(20) (no wait on the previous epilogue's write-through stores), phase prologue ends with vmcnt(0)
# baseline (speedup 1.0000x reference)
; #define PG8_STAGE(bufoff, gbase, voff) do { _Pragma("unroll") for (int _i = 0; _i < 2; ++_i) \
;         __builtin_amdgcn_global_load_lds((const unsigned*)((const char*)(gbase) + (voff)[_i]), (PG8_LAS unsigned*)(lds + (bufoff) + ldsw + _i * 8192), 16, 0, 0); } while (0)
; #define PG8_WAIT_V(n) asm volatile("s_waitcnt vmcnt(" #n ")" ::: "memory")
; #define PG8_BAR __builtin_amdgcn_s_barrier()
; template <class Epi, class Sched, bool ALIGN_EPI = false, bool SP2 = false>
; __device__ __forceinline__ void gemm_phase(PG8_LAS unsigned char* lds, const Gemm g, const Sched& S, const Epi& E) {
;     const int tid = threadIdx.x, wid = __builtin_amdgcn_readfirstlane(tid >> 6), lane = tid & 63, wr = wid >> 2, wc = wid & 3, fr = lane & 15, fq = lane >> 4;
;     const int K = g.K, nt = K / BK;
;     unsigned voffA[2], voffB[2];
; #pragma unroll
;     for (int i = 0; i < 2; ++i) { int R, C; stage_rc(tid * 16 + i * 8192, R, C); const int Rb = Epi::PERM ? ((R & ~31) + perm32(R & 31)) : R;
;         voffA[i] = (unsigned)(R * K + C) * 2u; voffB[i] = (unsigned)(Rb * K + C) * 2u; }
;     const size_t kstep = (size_t)(BK * 2);
;     const size_t hstep = (size_t)HALF * K * 2;
;     const size_t tstep = 2 * hstep;
;     const unsigned ldsw = (unsigned)wid * 1024u;
;     const int aoff = lds_byte(wr * 64 + fr, fq * 8), boff = lds_byte(wc * 32 + fr, fq * 8);
;     ...
;         PG8_STAGE(PG8_SB(0, 0), cB, voffB); PG8_STAGE(PG8_SB(0, 1), cB + hstep, voffB); PG8_STAGE(PG8_SA(0, 0), cA, voffA); PG8_STAGE(PG8_SA(0, 1), cA + hstep, voffA);
;         if (wr == 1) PG8_BAR;
;         PG8_WAIT_V(2); PG8_BAR;
;         PG8_STAGE(PG8_SB(1, 0), cB + kstep, voffB); PG8_STAGE(PG8_SA(1, 0), cA + kstep, voffA); PG8_STAGE(PG8_SB(1, 1), cB + hstep + kstep, voffB);
;         PG8_WAIT_V(6); PG8_BAR;
.LBB0_362:
	s_mov_b64 s[12:13], 0x80
	s_add_i32 m0, s28, 0x18000
	v_lshl_add_u64 v[8:9], v[8:9], 0, s[12:13]
	s_waitcnt vmcnt(2)
	s_barrier
	global_load_lds_dwordx4 v[8:9], off
	v_lshl_add_u64 v[4:5], v[4:5], 0, s[12:13]
	s_add_i32 m0, s28, 0x1a000
	s_add_i32 s34, s28, 0x8000
	global_load_lds_dwordx4 v[4:5], off
	v_lshl_add_u64 v[4:5], v[6:7], 0, s[12:13]
	s_mov_b32 m0, s34
	s_add_i32 s35, s28, 0xa000
	global_load_lds_dwordx4 v[4:5], off
	v_lshl_add_u64 v[4:5], v[10:11], 0, s[12:13]
	s_mov_b32 m0, s35
	v_lshl_add_u64 v[2:3], v[2:3], 0, s[12:13]
	global_load_lds_dwordx4 v[4:5], off
	s_add_i32 m0, s28, 0x1c000
	v_lshl_add_u64 v[0:1], v[0:1], 0, s[12:13]
	global_load_lds_dwordx4 v[2:3], off
	s_add_i32 m0, s28, 0x1e000
	s_lshr_b32 s1, s1, 26
	global_load_lds_dwordx4 v[0:1], off
	v_and_b32_e32 v0, 15, v254
	s_add_i32 s1, s0, s1
	v_lshlrev_b32_e32 v1, 1, v14
	v_lshlrev_b32_e32 v2, 2, v254
	s_ashr_i32 s36, s1, 6
	v_lshl_or_b32 v146, s15, 6, v0
	v_lshl_or_b32 v0, v0, 6, v1
	s_lshl_b32 s1, s15, 13
	v_and_b32_e32 v2, 32, v2
	v_bitop3_b32 v3, v0, s1, v2 bitop3:0xde
	s_lshl_b32 s1, s14, 5
	s_sext_i32_i16 s61, s2
	s_and_b32 s1, s1, 0x60
	v_lshlrev_b32_e32 v0, 6, v254
	s_movk_i32 s2, 0x3c0
	v_and_or_b32 v0, v0, s2, v1
	s_lshl_b32 s2, s1, 7
	v_bitop3_b32 v147, s2, v0, v2 bitop3:0xf6
	v_add_u32_e32 v0, v17, v16
	v_mul_lo_u32 v0, s0, v0
	v_lshlrev_b32_e32 v0, 1, v0
	v_add3_u32 v0, v12, v0, v13
	v_mov_b32_e32 v1, v133
	s_cmp_gt_i32 s0, 63
	v_lshl_add_u64 v[136:137], s[6:7], 0, v[0:1]
	v_add_u32_e32 v0, v15, v16
	s_cselect_b64 s[14:15], -1, 0
	s_add_i32 s37, s36, -2
	v_mul_lo_u32 v0, s0, v0
	s_waitcnt vmcnt(0)
	s_cmpk_lt_u32 s3, 0x100
	v_lshlrev_b32_e32 v0, 1, v0
	s_cselect_b64 s[20:21], -1, 0
	v_add3_u32 v0, v12, v0, v13
	s_add_i32 s40, 0, 0x10000
	s_add_i32 s41, 0, 0x14000
	s_ashr_i32 s38, s94, 31
	s_mov_b32 s39, s94
	v_or_b32_e32 v148, s1, v14
	v_lshl_add_u64 v[138:139], s[6:7], 0, v[0:1]
	v_mov_b64_e32 v[140:141], 0xb00
	v_mov_b64_e32 v[142:143], 0xaff
	v_add_u32_e32 v149, s40, v147
	v_add_u32_e32 v150, s41, v147
	v_add_u32_e32 v151, 0, v3
	v_mov_b32_e32 v152, 0x358637bd
	s_mov_b32 s50, 0x800000
	s_movk_i32 s51, 0x1600
	s_barrier
	s_branch .LBB0_365

; #define PG8_STAGE(bufoff, gbase, voff) do { _Pragma("unroll") for (int _i = 0; _i < 2; ++_i) \
;         __builtin_amdgcn_global_load_lds((const unsigned*)((const char*)(gbase) + (voff)[_i]), (PG8_LAS unsigned*)(lds + (bufoff) + ldsw + _i * 8192), 16, 0, 0); } while (0)
; #define PG8_LDA(dst, b, h) do { _Pragma("unroll") for (int m = 0; m < 4; ++m) _Pragma("unroll") for (int k = 0; k < 2; ++k) dst[m][k] = *(const PG8_LAS bf16x8*)(lds + PG8_SA(b, h) + aoff + m * 2048 + k * 1024); } while (0)
; #define PG8_LDB(dst, b, h) do { _Pragma("unroll") for (int n = 0; n < 2; ++n) _Pragma("unroll") for (int k = 0; k < 2; ++k) dst[n][k] = *(const PG8_LAS bf16x8*)(lds + PG8_SB(b, h) + boff + n * 2048 + k * 1024); } while (0)
; #define PG8_MMA(ai, bj, At, Bt) do { __builtin_amdgcn_s_setprio(1); _Pragma("unroll") for (int m = 0; m < 4; ++m) _Pragma("unroll") for (int n = 0; n < 2; ++n) _Pragma("unroll") for (int k = 0; k < 2; ++k) \
;         acc[ai][bj][m][n] = __builtin_amdgcn_mfma_f32_16x16x32_bf16(Bt[n][k], At[m][k], acc[ai][bj][m][n], 0, 0, 0); __builtin_amdgcn_s_setprio(0); } while (0)
; #define PG8_WAIT_V(n) asm volatile("s_waitcnt vmcnt(" #n ")" ::: "memory")
; #define PG8_BAR __builtin_amdgcn_s_barrier()
; template <class Epi, class Sched, bool ALIGN_EPI = false, bool SP2 = false>
; __device__ __forceinline__ void gemm_phase(PG8_LAS unsigned char* lds, const Gemm g, const Sched& S, const Epi& E) {
;     ...
;         for (int t = 0; t < nt; t += 2) {
;             const bool last = (t == nt - 2);
;             const char* a1 = cA + (size_t)(t + 1) * kstep;
;             const char* a2 = last ? nA : cA + (size_t)(t + 2) * kstep; const char* b2 = last ? nB : cB + (size_t)(t + 2) * kstep;
;             const char* a3 = a2 + kstep; const char* b3 = b2 + kstep;
;             if (last && has_next) S.a_ready(nxt);
;             if constexpr (SP2) {
;             PG8_LDB(B0, 0, 0); PG8_LDB(B1, 0, 1); PG8_SCHED; PG8_LDA(At, 0, 0); PG8_STAGE(PG8_SA(1, 1), a1 + hstep, voffA);
;             PG8_WAIT_V(8); PG8_WAIT_L(0); PG8_BAR; PG8_MMA(0, 0, At, B0); PG8_MMA(0, 1, At, B1); PG8_BAR; PG8_SCHED;
;             PG8_LDA(At, 0, 1); PG8_STAGE(PG8_SB(0, 0), b2, voffB); PG8_STAGE(PG8_SB(0, 1), b2 + hstep, voffB); PG8_STAGE(PG8_SA(0, 0), a2, voffA);
;             PG8_WAIT_V(8); PG8_WAIT_L(0); PG8_BAR; PG8_MMA(1, 0, At, B0); PG8_MMA(1, 1, At, B1); PG8_BAR; PG8_SCHED;
.LBB0_371:
	s_andn2_b64 vcc, exec, s[14:15]
	s_cbranch_vccnz .LBB0_374
	s_add_u32 s24, s24, 0x80
	s_addc_u32 s25, s25, 0
	s_add_u32 s62, s26, 0x100
	s_addc_u32 s63, s27, 0
	s_mov_b32 s26, 0
	ds_read_b128 v[154:157], v149
	ds_read_b128 v[158:161], v149 offset:1024
	ds_read_b128 v[162:165], v149 offset:2048
	ds_read_b128 v[166:169], v149 offset:3072
	ds_read_b128 v[170:173], v150
	ds_read_b128 v[174:177], v150 offset:1024
	ds_read_b128 v[180:183], v150 offset:2048
	ds_read_b128 v[184:187], v150 offset:3072
	s_add_i32 s64, s26, 2
	s_add_u32 s65, s24, 0x80
	s_addc_u32 s27, s25, 0
	s_cmp_eq_u32 s37, s26
	s_cselect_b32 s26, s0, s65
	s_cselect_b32 s27, s1, s27
	s_cselect_b32 s67, s23, s63
	s_cselect_b32 s66, s22, s62
	v_lshl_add_u64 v[144:145], s[24:25], 0, v[136:137]
	s_add_i32 m0, s28, 0xc000
	ds_read_b128 v[188:191], v151
	ds_read_b128 v[192:195], v151 offset:1024
	ds_read_b128 v[196:199], v151 offset:2048
	ds_read_b128 v[200:203], v151 offset:3072
	ds_read_b128 v[204:207], v151 offset:4096
	ds_read_b128 v[208:211], v151 offset:5120
	ds_read_b128 v[212:215], v151 offset:6144
	ds_read_b128 v[216:219], v151 offset:7168
	global_load_lds_dwordx4 v[144:145], off
	v_lshl_add_u64 v[144:145], s[24:25], 0, v[138:139]
	s_add_i32 m0, s28, 0xe000
	s_nop 0
	global_load_lds_dwordx4 v[144:145], off
	s_waitcnt vmcnt(14)
	s_waitcnt lgkmcnt(0)
	s_barrier
	s_setprio 1
	s_waitcnt lgkmcnt(0)
	v_mfma_f32_16x16x32_bf16 v[116:119], v[154:157], v[188:191], 0
	v_mfma_f32_16x16x32_bf16 v[112:115], v[162:165], v[188:191], 0
	v_mfma_f32_16x16x32_bf16 v[100:103], v[154:157], v[196:199], 0
	v_mfma_f32_16x16x32_bf16 v[96:99], v[162:165], v[196:199], 0
	v_mfma_f32_16x16x32_bf16 v[84:87], v[154:157], v[204:207], 0
	v_mfma_f32_16x16x32_bf16 v[80:83], v[162:165], v[204:207], 0
	v_mfma_f32_16x16x32_bf16 v[68:71], v[154:157], v[212:215], 0
	v_mfma_f32_16x16x32_bf16 v[64:67], v[162:165], v[212:215], 0
	v_mfma_f32_16x16x32_bf16 v[116:119], v[158:161], v[192:195], v[116:119]
	v_mfma_f32_16x16x32_bf16 v[112:115], v[166:169], v[192:195], v[112:115]
	v_mfma_f32_16x16x32_bf16 v[100:103], v[158:161], v[200:203], v[100:103]
	v_mfma_f32_16x16x32_bf16 v[96:99], v[166:169], v[200:203], v[96:99]
	v_mfma_f32_16x16x32_bf16 v[84:87], v[158:161], v[208:211], v[84:87]
	v_mfma_f32_16x16x32_bf16 v[80:83], v[166:169], v[208:211], v[80:83]
	v_mfma_f32_16x16x32_bf16 v[68:71], v[158:161], v[216:219], v[68:71]
	v_mfma_f32_16x16x32_bf16 v[64:67], v[166:169], v[216:219], v[64:67]
	s_setprio 0
	s_setprio 1
	v_mfma_f32_16x16x32_bf16 v[124:127], v[170:173], v[188:191], 0
	v_mfma_f32_16x16x32_bf16 v[120:123], v[180:183], v[188:191], 0
	v_mfma_f32_16x16x32_bf16 v[108:111], v[170:173], v[196:199], 0
	v_mfma_f32_16x16x32_bf16 v[104:107], v[180:183], v[196:199], 0
	v_mfma_f32_16x16x32_bf16 v[92:95], v[170:173], v[204:207], 0
	v_mfma_f32_16x16x32_bf16 v[88:91], v[180:183], v[204:207], 0
	v_mfma_f32_16x16x32_bf16 v[76:79], v[170:173], v[212:215], 0
	v_mfma_f32_16x16x32_bf16 v[72:75], v[180:183], v[212:215], 0
	v_mfma_f32_16x16x32_bf16 v[124:127], v[174:177], v[192:195], v[124:127]
	v_mfma_f32_16x16x32_bf16 v[120:123], v[184:187], v[192:195], v[120:123]
	v_mfma_f32_16x16x32_bf16 v[108:111], v[174:177], v[200:203], v[108:111]
	v_mfma_f32_16x16x32_bf16 v[104:107], v[184:187], v[200:203], v[104:107]
	v_mfma_f32_16x16x32_bf16 v[92:95], v[174:177], v[208:211], v[92:95]
	v_mfma_f32_16x16x32_bf16 v[88:91], v[184:187], v[208:211], v[88:91]
	v_mfma_f32_16x16x32_bf16 v[76:79], v[174:177], v[216:219], v[76:79]
	v_mfma_f32_16x16x32_bf16 v[72:75], v[184:187], v[216:219], v[72:75]
	s_setprio 0
	s_barrier
	s_add_i32 s65, s40, s16
	v_lshl_add_u64 v[144:145], s[66:67], 0, v[132:133]
	s_mov_b32 m0, s65
	ds_read_b128 v[188:191], v151 offset:16384
	ds_read_b128 v[192:195], v151 offset:17408
	ds_read_b128 v[196:199], v151 offset:18432
	ds_read_b128 v[200:203], v151 offset:19456
	ds_read_b128 v[204:207], v151 offset:20480
	ds_read_b128 v[208:211], v151 offset:21504
	ds_read_b128 v[212:215], v151 offset:22528
	ds_read_b128 v[216:219], v151 offset:23552
	global_load_lds_dwordx4 v[144:145], off
	s_add_i32 m0, s65, 0x2000
	v_lshl_add_u64 v[178:179], s[66:67], 0, v[128:129]
	s_add_u32 s66, s66, s6
	s_addc_u32 s67, s67, s7
	s_add_i32 s65, s41, s16
	global_load_lds_dwordx4 v[178:179], off
	v_lshl_add_u64 v[220:221], s[66:67], 0, v[132:133]
	s_mov_b32 m0, s65
	v_lshl_add_u64 v[222:223], s[66:67], 0, v[128:129]
	global_load_lds_dwordx4 v[220:221], off
	s_add_i32 m0, s65, 0x2000
	v_lshl_add_u64 v[224:225], s[26:27], 0, v[134:135]
	global_load_lds_dwordx4 v[222:223], off
	s_mov_b32 m0, s28
	v_lshl_add_u64 v[226:227], s[26:27], 0, v[130:131]
	global_load_lds_dwordx4 v[224:225], off
	s_mov_b32 m0, s29
	s_nop 0
	global_load_lds_dwordx4 v[226:227], off
	s_waitcnt vmcnt(20)
	s_waitcnt lgkmcnt(0)
	s_barrier
; #define PG8_STAGE(bufoff, gbase, voff) do { _Pragma("unroll") for (int _i = 0; _i < 2; ++_i) \
;         __builtin_amdgcn_global_load_lds((const unsigned*)((const char*)(gbase) + (voff)[_i]), (PG8_LAS unsigned*)(lds + (bufoff) + ldsw + _i * 8192), 16, 0, 0); } while (0)
; #define PG8_LDA(dst, b, h) do { _Pragma("unroll") for (int m = 0; m < 4; ++m) _Pragma("unroll") for (int k = 0; k < 2; ++k) dst[m][k] = *(const PG8_LAS bf16x8*)(lds + PG8_SA(b, h) + aoff + m * 2048 + k * 1024); } while (0)
; #define PG8_LDB(dst, b, h) do { _Pragma("unroll") for (int n = 0; n < 2; ++n) _Pragma("unroll") for (int k = 0; k < 2; ++k) dst[n][k] = *(const PG8_LAS bf16x8*)(lds + PG8_SB(b, h) + boff + n * 2048 + k * 1024); } while (0)
; #define PG8_MMA(ai, bj, At, Bt) do { __builtin_amdgcn_s_setprio(1); _Pragma("unroll") for (int m = 0; m < 4; ++m) _Pragma("unroll") for (int n = 0; n < 2; ++n) _Pragma("unroll") for (int k = 0; k < 2; ++k) \
;         acc[ai][bj][m][n] = __builtin_amdgcn_mfma_f32_16x16x32_bf16(Bt[n][k], At[m][k], acc[ai][bj][m][n], 0, 0, 0); __builtin_amdgcn_s_setprio(0); } while (0)
; #define PG8_WAIT_V(n) asm volatile("s_waitcnt vmcnt(" #n ")" ::: "memory")
; #define PG8_WAIT_L(n) asm volatile("s_waitcnt lgkmcnt(" #n ")" ::: "memory")
; #define PG8_BAR __builtin_amdgcn_s_barrier()
; #define PG8_SCHED __builtin_amdgcn_sched_barrier(0)
; template <class Epi, class Sched, bool ALIGN_EPI = false, bool SP2 = false>
; __device__ __forceinline__ void gemm_phase(PG8_LAS unsigned char* lds, const Gemm g, const Sched& S, const Epi& E) {
;     ...
;             PG8_WAIT_V(8); PG8_WAIT_L(0); PG8_BAR; PG8_MMA(1, 0, At, B0); PG8_MMA(1, 1, At, B1); PG8_BAR; PG8_SCHED;
;             PG8_LDB(B0, 1, 0); PG8_LDB(B1, 1, 1); PG8_SCHED; PG8_LDA(At, 1, 0); PG8_STAGE(PG8_SA(0, 1), a2 + hstep, voffA);
;             PG8_WAIT_V(8); PG8_WAIT_L(0); PG8_BAR; PG8_MMA(0, 0, At, B0); PG8_MMA(0, 1, At, B1); PG8_BAR; PG8_SCHED;
;             PG8_LDA(At, 1, 1); PG8_STAGE(PG8_SB(1, 0), b3, voffB); PG8_STAGE(PG8_SB(1, 1), b3 + hstep, voffB); PG8_STAGE(PG8_SA(1, 0), a3, voffA);
;             PG8_WAIT_V(8); PG8_WAIT_L(0); PG8_BAR; PG8_MMA(1, 0, At, B0); PG8_MMA(1, 1, At, B1); PG8_BAR; PG8_SCHED;
	s_setprio 1
	s_waitcnt lgkmcnt(0)
	v_mfma_f32_16x16x32_bf16 v[52:55], v[154:157], v[188:191], 0
	v_mfma_f32_16x16x32_bf16 v[48:51], v[162:165], v[188:191], 0
	v_mfma_f32_16x16x32_bf16 v[36:39], v[154:157], v[196:199], 0
	v_mfma_f32_16x16x32_bf16 v[32:35], v[162:165], v[196:199], 0
	v_mfma_f32_16x16x32_bf16 v[20:23], v[154:157], v[204:207], 0
	v_mfma_f32_16x16x32_bf16 v[16:19], v[162:165], v[204:207], 0
	v_mfma_f32_16x16x32_bf16 v[4:7], v[154:157], v[212:215], 0
	v_mfma_f32_16x16x32_bf16 v[0:3], v[162:165], v[212:215], 0
	v_mfma_f32_16x16x32_bf16 v[52:55], v[158:161], v[192:195], v[52:55]
	v_mfma_f32_16x16x32_bf16 v[48:51], v[166:169], v[192:195], v[48:51]
	v_mfma_f32_16x16x32_bf16 v[36:39], v[158:161], v[200:203], v[36:39]
	v_mfma_f32_16x16x32_bf16 v[32:35], v[166:169], v[200:203], v[32:35]
	v_mfma_f32_16x16x32_bf16 v[20:23], v[158:161], v[208:211], v[20:23]
	v_mfma_f32_16x16x32_bf16 v[16:19], v[166:169], v[208:211], v[16:19]
	v_mfma_f32_16x16x32_bf16 v[4:7], v[158:161], v[216:219], v[4:7]
	v_mfma_f32_16x16x32_bf16 v[0:3], v[166:169], v[216:219], v[0:3]
	s_setprio 0
	s_setprio 1
	v_mfma_f32_16x16x32_bf16 v[60:63], v[170:173], v[188:191], 0
	v_mfma_f32_16x16x32_bf16 v[56:59], v[180:183], v[188:191], 0
	v_mfma_f32_16x16x32_bf16 v[44:47], v[170:173], v[196:199], 0
	v_mfma_f32_16x16x32_bf16 v[40:43], v[180:183], v[196:199], 0
	v_mfma_f32_16x16x32_bf16 v[28:31], v[170:173], v[204:207], 0
	v_mfma_f32_16x16x32_bf16 v[24:27], v[180:183], v[204:207], 0
	v_mfma_f32_16x16x32_bf16 v[12:15], v[170:173], v[212:215], 0
	v_mfma_f32_16x16x32_bf16 v[8:11], v[180:183], v[212:215], 0
	v_mfma_f32_16x16x32_bf16 v[60:63], v[174:177], v[192:195], v[60:63]
	v_mfma_f32_16x16x32_bf16 v[56:59], v[184:187], v[192:195], v[56:59]
	v_mfma_f32_16x16x32_bf16 v[44:47], v[174:177], v[200:203], v[44:47]
	v_mfma_f32_16x16x32_bf16 v[40:43], v[184:187], v[200:203], v[40:43]
	v_mfma_f32_16x16x32_bf16 v[28:31], v[174:177], v[208:211], v[28:31]
	v_mfma_f32_16x16x32_bf16 v[24:27], v[184:187], v[208:211], v[24:27]
	v_mfma_f32_16x16x32_bf16 v[12:15], v[174:177], v[216:219], v[12:15]
	v_mfma_f32_16x16x32_bf16 v[8:11], v[184:187], v[216:219], v[8:11]
	s_setprio 0
	s_barrier
	s_add_i32 s65, 0, 0x18000
	v_add_u32_e32 v153, s65, v147
	s_add_i32 s66, 0, 0x1c000
	ds_read_b128 v[154:157], v153
	ds_read_b128 v[158:161], v153 offset:1024
	ds_read_b128 v[162:165], v153 offset:2048
	ds_read_b128 v[166:169], v153 offset:3072
	v_add_u32_e32 v153, s66, v147
	ds_read_b128 v[170:173], v153
	ds_read_b128 v[174:177], v153 offset:1024
	ds_read_b128 v[180:183], v153 offset:2048
	ds_read_b128 v[184:187], v153 offset:3072
	s_add_u32 s26, s26, s6
	s_addc_u32 s27, s27, s7
	s_mov_b32 m0, s30
	v_lshl_add_u64 v[228:229], s[26:27], 0, v[134:135]
	ds_read_b128 v[188:191], v151 offset:32768
	ds_read_b128 v[192:195], v151 offset:33792
	ds_read_b128 v[196:199], v151 offset:34816
	ds_read_b128 v[200:203], v151 offset:35840
	ds_read_b128 v[204:207], v151 offset:36864
	ds_read_b128 v[208:211], v151 offset:37888
	ds_read_b128 v[212:215], v151 offset:38912
	ds_read_b128 v[216:219], v151 offset:39936
	global_load_lds_dwordx4 v[228:229], off
	v_lshl_add_u64 v[228:229], s[26:27], 0, v[130:131]
	s_mov_b32 m0, s31
	s_nop 0
	global_load_lds_dwordx4 v[228:229], off
	s_waitcnt vmcnt(8)
	s_waitcnt lgkmcnt(0)
	s_barrier
	s_setprio 1
	s_waitcnt lgkmcnt(0)
	v_mfma_f32_16x16x32_bf16 v[116:119], v[154:157], v[188:191], v[116:119]
	v_mfma_f32_16x16x32_bf16 v[112:115], v[162:165], v[188:191], v[112:115]
	v_mfma_f32_16x16x32_bf16 v[100:103], v[154:157], v[196:199], v[100:103]
	v_mfma_f32_16x16x32_bf16 v[96:99], v[162:165], v[196:199], v[96:99]
	v_mfma_f32_16x16x32_bf16 v[84:87], v[154:157], v[204:207], v[84:87]
	v_mfma_f32_16x16x32_bf16 v[80:83], v[162:165], v[204:207], v[80:83]
	v_mfma_f32_16x16x32_bf16 v[68:71], v[154:157], v[212:215], v[68:71]
	v_mfma_f32_16x16x32_bf16 v[64:67], v[162:165], v[212:215], v[64:67]
	v_mfma_f32_16x16x32_bf16 v[116:119], v[158:161], v[192:195], v[116:119]
	v_mfma_f32_16x16x32_bf16 v[112:115], v[166:169], v[192:195], v[112:115]
	v_mfma_f32_16x16x32_bf16 v[100:103], v[158:161], v[200:203], v[100:103]
	v_mfma_f32_16x16x32_bf16 v[96:99], v[166:169], v[200:203], v[96:99]
	v_mfma_f32_16x16x32_bf16 v[84:87], v[158:161], v[208:211], v[84:87]
	v_mfma_f32_16x16x32_bf16 v[80:83], v[166:169], v[208:211], v[80:83]
	v_mfma_f32_16x16x32_bf16 v[68:71], v[158:161], v[216:219], v[68:71]
	v_mfma_f32_16x16x32_bf16 v[64:67], v[166:169], v[216:219], v[64:67]
	s_setprio 0
	s_setprio 1
	v_mfma_f32_16x16x32_bf16 v[124:127], v[170:173], v[188:191], v[124:127]
	v_mfma_f32_16x16x32_bf16 v[120:123], v[180:183], v[188:191], v[120:123]
	v_mfma_f32_16x16x32_bf16 v[108:111], v[170:173], v[196:199], v[108:111]
	v_mfma_f32_16x16x32_bf16 v[104:107], v[180:183], v[196:199], v[104:107]
	v_mfma_f32_16x16x32_bf16 v[92:95], v[170:173], v[204:207], v[92:95]
	v_mfma_f32_16x16x32_bf16 v[88:91], v[180:183], v[204:207], v[88:91]
	v_mfma_f32_16x16x32_bf16 v[76:79], v[170:173], v[212:215], v[76:79]
	v_mfma_f32_16x16x32_bf16 v[72:75], v[180:183], v[212:215], v[72:75]
	v_mfma_f32_16x16x32_bf16 v[124:127], v[174:177], v[192:195], v[124:127]
	v_mfma_f32_16x16x32_bf16 v[120:123], v[184:187], v[192:195], v[120:123]
	v_mfma_f32_16x16x32_bf16 v[108:111], v[174:177], v[200:203], v[108:111]
	v_mfma_f32_16x16x32_bf16 v[104:107], v[184:187], v[200:203], v[104:107]
	v_mfma_f32_16x16x32_bf16 v[92:95], v[174:177], v[208:211], v[92:95]
	v_mfma_f32_16x16x32_bf16 v[88:91], v[184:187], v[208:211], v[88:91]
	v_mfma_f32_16x16x32_bf16 v[76:79], v[174:177], v[216:219], v[76:79]
	v_mfma_f32_16x16x32_bf16 v[72:75], v[184:187], v[216:219], v[72:75]
	s_setprio 0
	s_barrier
; #define PG8_STAGE(bufoff, gbase, voff) do { _Pragma("unroll") for (int _i = 0; _i < 2; ++_i) \
;         __builtin_amdgcn_global_load_lds((const unsigned*)((const char*)(gbase) + (voff)[_i]), (PG8_LAS unsigned*)(lds + (bufoff) + ldsw + _i * 8192), 16, 0, 0); } while (0)
; #define PG8_LDA(dst, b, h) do { _Pragma("unroll") for (int m = 0; m < 4; ++m) _Pragma("unroll") for (int k = 0; k < 2; ++k) dst[m][k] = *(const PG8_LAS bf16x8*)(lds + PG8_SA(b, h) + aoff + m * 2048 + k * 1024); } while (0)
; #define PG8_MMA(ai, bj, At, Bt) do { __builtin_amdgcn_s_setprio(1); _Pragma("unroll") for (int m = 0; m < 4; ++m) _Pragma("unroll") for (int n = 0; n < 2; ++n) _Pragma("unroll") for (int k = 0; k < 2; ++k) \
;         acc[ai][bj][m][n] = __builtin_amdgcn_mfma_f32_16x16x32_bf16(Bt[n][k], At[m][k], acc[ai][bj][m][n], 0, 0, 0); __builtin_amdgcn_s_setprio(0); } while (0)
; #define PG8_WAIT_V(n) asm volatile("s_waitcnt vmcnt(" #n ")" ::: "memory")
; #define PG8_WAIT_L(n) asm volatile("s_waitcnt lgkmcnt(" #n ")" ::: "memory")
; #define PG8_BAR __builtin_amdgcn_s_barrier()
; #define PG8_SCHED __builtin_amdgcn_sched_barrier(0)
; template <class Epi, class Sched, bool ALIGN_EPI = false, bool SP2 = false>
; __device__ __forceinline__ void gemm_phase(PG8_LAS unsigned char* lds, const Gemm g, const Sched& S, const Epi& E) {
;     ...
;             PG8_LDA(At, 1, 1); PG8_STAGE(PG8_SB(1, 0), b3, voffB); PG8_STAGE(PG8_SB(1, 1), b3 + hstep, voffB); PG8_STAGE(PG8_SA(1, 0), a3, voffA);
;             PG8_WAIT_V(8); PG8_WAIT_L(0); PG8_BAR; PG8_MMA(1, 0, At, B0); PG8_MMA(1, 1, At, B1); PG8_BAR; PG8_SCHED;
	s_add_i32 s26, s65, s16
	v_lshl_add_u64 v[144:145], v[144:145], 0, s[12:13]
	s_mov_b32 m0, s26
	ds_read_b128 v[188:191], v151 offset:49152
	ds_read_b128 v[192:195], v151 offset:50176
	ds_read_b128 v[196:199], v151 offset:51200
	ds_read_b128 v[200:203], v151 offset:52224
	ds_read_b128 v[204:207], v151 offset:53248
	ds_read_b128 v[208:211], v151 offset:54272
	ds_read_b128 v[212:215], v151 offset:55296
	ds_read_b128 v[216:219], v151 offset:56320
	global_load_lds_dwordx4 v[144:145], off
	v_lshl_add_u64 v[144:145], v[178:179], 0, s[12:13]
	s_add_i32 m0, s26, 0x2000
	s_add_i32 s26, s66, s16
	global_load_lds_dwordx4 v[144:145], off
	v_lshl_add_u64 v[144:145], v[220:221], 0, s[12:13]
	s_mov_b32 m0, s26
	s_nop 0
	global_load_lds_dwordx4 v[144:145], off
	v_lshl_add_u64 v[144:145], v[222:223], 0, s[12:13]
	s_add_i32 m0, s26, 0x2000
	s_nop 0
	global_load_lds_dwordx4 v[144:145], off
	v_lshl_add_u64 v[144:145], v[224:225], 0, s[12:13]
	s_mov_b32 m0, s34
	s_nop 0
	global_load_lds_dwordx4 v[144:145], off
	v_lshl_add_u64 v[144:145], v[226:227], 0, s[12:13]
	s_mov_b32 m0, s35
	s_nop 0
	global_load_lds_dwordx4 v[144:145], off
	s_waitcnt vmcnt(8)
	s_waitcnt lgkmcnt(0)
	s_barrier
	s_setprio 1
	s_waitcnt lgkmcnt(0)
	v_mfma_f32_16x16x32_bf16 v[52:55], v[154:157], v[188:191], v[52:55]
	v_mfma_f32_16x16x32_bf16 v[48:51], v[162:165], v[188:191], v[48:51]
	v_mfma_f32_16x16x32_bf16 v[36:39], v[154:157], v[196:199], v[36:39]
	v_mfma_f32_16x16x32_bf16 v[32:35], v[162:165], v[196:199], v[32:35]
	v_mfma_f32_16x16x32_bf16 v[20:23], v[154:157], v[204:207], v[20:23]
	v_mfma_f32_16x16x32_bf16 v[16:19], v[162:165], v[204:207], v[16:19]
	v_mfma_f32_16x16x32_bf16 v[4:7], v[154:157], v[212:215], v[4:7]
	v_mfma_f32_16x16x32_bf16 v[0:3], v[162:165], v[212:215], v[0:3]
	v_mfma_f32_16x16x32_bf16 v[52:55], v[158:161], v[192:195], v[52:55]
	v_mfma_f32_16x16x32_bf16 v[48:51], v[166:169], v[192:195], v[48:51]
	v_mfma_f32_16x16x32_bf16 v[36:39], v[158:161], v[200:203], v[36:39]
	v_mfma_f32_16x16x32_bf16 v[32:35], v[166:169], v[200:203], v[32:35]
	v_mfma_f32_16x16x32_bf16 v[20:23], v[158:161], v[208:211], v[20:23]
	v_mfma_f32_16x16x32_bf16 v[16:19], v[166:169], v[208:211], v[16:19]
	v_mfma_f32_16x16x32_bf16 v[4:7], v[158:161], v[216:219], v[4:7]
	v_mfma_f32_16x16x32_bf16 v[0:3], v[166:169], v[216:219], v[0:3]
	s_setprio 0
	s_setprio 1
	v_mfma_f32_16x16x32_bf16 v[60:63], v[170:173], v[188:191], v[60:63]
	v_mfma_f32_16x16x32_bf16 v[56:59], v[180:183], v[188:191], v[56:59]
	v_mfma_f32_16x16x32_bf16 v[44:47], v[170:173], v[196:199], v[44:47]
	v_mfma_f32_16x16x32_bf16 v[40:43], v[180:183], v[196:199], v[40:43]
	v_mfma_f32_16x16x32_bf16 v[28:31], v[170:173], v[204:207], v[28:31]
	v_mfma_f32_16x16x32_bf16 v[24:27], v[180:183], v[204:207], v[24:27]
	v_mfma_f32_16x16x32_bf16 v[12:15], v[170:173], v[212:215], v[12:15]
	v_mfma_f32_16x16x32_bf16 v[8:11], v[180:183], v[212:215], v[8:11]
	v_mfma_f32_16x16x32_bf16 v[60:63], v[174:177], v[192:195], v[60:63]
	v_mfma_f32_16x16x32_bf16 v[56:59], v[184:187], v[192:195], v[56:59]
	v_mfma_f32_16x16x32_bf16 v[44:47], v[174:177], v[200:203], v[44:47]
	v_mfma_f32_16x16x32_bf16 v[40:43], v[184:187], v[200:203], v[40:43]
	v_mfma_f32_16x16x32_bf16 v[28:31], v[174:177], v[208:211], v[28:31]
	v_mfma_f32_16x16x32_bf16 v[24:27], v[184:187], v[208:211], v[24:27]
	v_mfma_f32_16x16x32_bf16 v[12:15], v[174:177], v[216:219], v[12:15]
	v_mfma_f32_16x16x32_bf16 v[8:11], v[184:187], v[216:219], v[8:11]
	s_setprio 0
	s_barrier
	s_add_u32 s24, s24, 0x100
	s_addc_u32 s25, s25, 0
	s_add_u32 s62, s62, 0x100
	s_addc_u32 s63, s63, 0
	s_cmp_ge_i32 s64, s36
	s_mov_b32 s26, s64
	s_cbranch_scc0 .LBB0_373
	s_branch .Lpeel_x0

; #define PG8_STAGE(bufoff, gbase, voff) do { _Pragma("unroll") for (int _i = 0; _i < 2; ++_i) \
;         __builtin_amdgcn_global_load_lds((const unsigned*)((const char*)(gbase) + (voff)[_i]), (PG8_LAS unsigned*)(lds + (bufoff) + ldsw + _i * 8192), 16, 0, 0); } while (0)
; #define PG8_WAIT_V(n) asm volatile("s_waitcnt vmcnt(" #n ")" ::: "memory")
; #define PG8_BAR __builtin_amdgcn_s_barrier()
; template <class Epi, class Sched, bool ALIGN_EPI = false, bool SP2 = false>
; __device__ __forceinline__ void gemm_phase(PG8_LAS unsigned char* lds, const Gemm g, const Sched& S, const Epi& E) {
;     ...
;     for (int i = 0; i < 2; ++i) { int R, C; stage_rc(tid * 16 + i * 8192, R, C); const int Rb = Epi::PERM ? ((R & ~31) + perm32(R & 31)) : R;
;         voffA[i] = (unsigned)(R * K + C) * 2u; voffB[i] = (unsigned)(Rb * K + C) * 2u; }
;     const size_t kstep = (size_t)(BK * 2);
;     const size_t hstep = (size_t)HALF * K * 2;
;     const size_t tstep = 2 * hstep;
;     const unsigned ldsw = (unsigned)wid * 1024u;
;     const int aoff = lds_byte(wr * 64 + fr, fq * 8), boff = lds_byte(wc * 32 + fr, fq * 8);
;     ...
;         PG8_STAGE(PG8_SB(1, 0), cB + kstep, voffB); PG8_STAGE(PG8_SA(1, 0), cA + kstep, voffA); PG8_STAGE(PG8_SB(1, 1), cB + hstep + kstep, voffB);
;         PG8_WAIT_V(6); PG8_BAR;
.LBB0_1306:
	s_mov_b64 s[14:15], 0x80
	s_add_i32 m0, s30, 0x18000
	v_lshl_add_u64 v[8:9], v[8:9], 0, s[14:15]
	s_waitcnt vmcnt(2)
	s_barrier
	global_load_lds_dwordx4 v[8:9], off
	v_lshl_add_u64 v[4:5], v[4:5], 0, s[14:15]
	s_add_i32 m0, s30, 0x1a000
	s_add_i32 s36, s30, 0x8000
	global_load_lds_dwordx4 v[4:5], off
	v_lshl_add_u64 v[4:5], v[6:7], 0, s[14:15]
	s_mov_b32 m0, s36
	s_add_i32 s37, s30, 0xa000
	global_load_lds_dwordx4 v[4:5], off
	v_lshl_add_u64 v[4:5], v[10:11], 0, s[14:15]
	s_mov_b32 m0, s37
	v_lshl_add_u64 v[2:3], v[2:3], 0, s[14:15]
	global_load_lds_dwordx4 v[4:5], off
	s_add_i32 m0, s30, 0x1c000
	v_lshl_add_u64 v[0:1], v[0:1], 0, s[14:15]
	global_load_lds_dwordx4 v[2:3], off
	s_add_i32 m0, s30, 0x1e000
	s_lshr_b32 s1, s1, 26
	global_load_lds_dwordx4 v[0:1], off
	v_and_b32_e32 v0, 15, v254
	s_add_i32 s1, s0, s1
	v_lshlrev_b32_e32 v1, 1, v14
	v_lshlrev_b32_e32 v2, 2, v254
	s_ashr_i32 s38, s1, 6
	v_lshl_or_b32 v146, s21, 6, v0
	v_lshl_or_b32 v0, v0, 6, v1
	s_lshl_b32 s1, s21, 13
	v_and_b32_e32 v2, 32, v2
	v_bitop3_b32 v3, v0, s1, v2 bitop3:0xde
	s_lshl_b32 s1, s20, 5
	s_sext_i32_i16 s61, s2
	s_and_b32 s1, s1, 0x60
	v_lshlrev_b32_e32 v0, 6, v254
	s_movk_i32 s2, 0x3c0
	v_and_or_b32 v0, v0, s2, v1
	s_lshl_b32 s2, s1, 7
	v_bitop3_b32 v147, s2, v0, v2 bitop3:0xf6
	v_add_u32_e32 v0, v17, v16
	v_mul_lo_u32 v0, s0, v0
	v_lshlrev_b32_e32 v0, 1, v0
	v_add3_u32 v0, v12, v0, v13
	v_mov_b32_e32 v1, v133
	s_cmp_gt_i32 s0, 63
	v_lshl_add_u64 v[136:137], s[8:9], 0, v[0:1]
	v_add_u32_e32 v0, v15, v16
	s_cselect_b64 s[20:21], -1, 0
	s_add_i32 s39, s38, -2
	v_mul_lo_u32 v0, s0, v0
	s_waitcnt vmcnt(0)
	s_cmpk_lt_u32 s3, 0x100
	v_lshlrev_b32_e32 v0, 1, v0
	s_cselect_b64 s[22:23], -1, 0
	v_add3_u32 v0, v12, v0, v13
	s_add_i32 s50, 0, 0x10000
	s_add_i32 s51, 0, 0x14000
	s_ashr_i32 s40, s94, 31
	s_mov_b32 s41, s94
	v_or_b32_e32 v148, s1, v14
	v_lshl_add_u64 v[138:139], s[8:9], 0, v[0:1]
	v_mov_b64_e32 v[140:141], 0xb00
	v_mov_b64_e32 v[142:143], 0xaff
	v_add_u32_e32 v149, s50, v147
	v_add_u32_e32 v150, s51, v147
	v_add_u32_e32 v151, 0, v3
	v_mov_b32_e32 v152, 0x358637bd
	s_mov_b32 s56, 0x800000
	s_movk_i32 s57, 0x1600
	s_barrier
	s_branch .LBB0_1309

; #define PG8_STAGE(bufoff, gbase, voff) do { _Pragma("unroll") for (int _i = 0; _i < 2; ++_i) \
;         __builtin_amdgcn_global_load_lds((const unsigned*)((const char*)(gbase) + (voff)[_i]), (PG8_LAS unsigned*)(lds + (bufoff) + ldsw + _i * 8192), 16, 0, 0); } while (0)
; #define PG8_LDA(dst, b, h) do { _Pragma("unroll") for (int m = 0; m < 4; ++m) _Pragma("unroll") for (int k = 0; k < 2; ++k) dst[m][k] = *(const PG8_LAS bf16x8*)(lds + PG8_SA(b, h) + aoff + m * 2048 + k * 1024); } while (0)
; #define PG8_LDB(dst, b, h) do { _Pragma("unroll") for (int n = 0; n < 2; ++n) _Pragma("unroll") for (int k = 0; k < 2; ++k) dst[n][k] = *(const PG8_LAS bf16x8*)(lds + PG8_SB(b, h) + boff + n * 2048 + k * 1024); } while (0)
; #define PG8_MMA(ai, bj, At, Bt) do { __builtin_amdgcn_s_setprio(1); _Pragma("unroll") for (int m = 0; m < 4; ++m) _Pragma("unroll") for (int n = 0; n < 2; ++n) _Pragma("unroll") for (int k = 0; k < 2; ++k) \
;         acc[ai][bj][m][n] = __builtin_amdgcn_mfma_f32_16x16x32_bf16(Bt[n][k], At[m][k], acc[ai][bj][m][n], 0, 0, 0); __builtin_amdgcn_s_setprio(0); } while (0)
; #define PG8_WAIT_V(n) asm volatile("s_waitcnt vmcnt(" #n ")" ::: "memory")
; #define PG8_WAIT_L(n) asm volatile("s_waitcnt lgkmcnt(" #n ")" ::: "memory")
; #define PG8_BAR __builtin_amdgcn_s_barrier()
; #define PG8_SCHED __builtin_amdgcn_sched_barrier(0)
; template <class Epi, class Sched, bool ALIGN_EPI = false, bool SP2 = false>
; __device__ __forceinline__ void gemm_phase(PG8_LAS unsigned char* lds, const Gemm g, const Sched& S, const Epi& E) {
;     ...
;             PG8_LDB(B0, 0, 0); PG8_LDB(B1, 0, 1); PG8_SCHED; PG8_LDA(At, 0, 0); PG8_STAGE(PG8_SA(1, 1), a1 + hstep, voffA);
;             PG8_WAIT_V(8); PG8_WAIT_L(0); PG8_BAR; PG8_MMA(0, 0, At, B0); PG8_MMA(0, 1, At, B1); PG8_BAR; PG8_SCHED;
;             PG8_LDA(At, 0, 1); PG8_STAGE(PG8_SB(0, 0), b2, voffB); PG8_STAGE(PG8_SB(0, 1), b2 + hstep, voffB); PG8_STAGE(PG8_SA(0, 0), a2, voffA);
;             PG8_WAIT_V(8); PG8_WAIT_L(0); PG8_BAR; PG8_MMA(1, 0, At, B0); PG8_MMA(1, 1, At, B1); PG8_BAR; PG8_SCHED;
.LBB0_1315:
	s_andn2_b64 vcc, exec, s[20:21]
	s_waitcnt vmcnt(0)
	s_cbranch_vccnz .LBB0_1318
	s_add_u32 s26, s26, 0x80
	s_addc_u32 s27, s27, 0
	s_add_u32 s62, s28, 0x100
	s_addc_u32 s63, s29, 0
	s_mov_b32 s28, 0
	ds_read_b128 v[154:157], v149
	ds_read_b128 v[158:161], v149 offset:1024
	ds_read_b128 v[162:165], v149 offset:2048
	ds_read_b128 v[166:169], v149 offset:3072
	ds_read_b128 v[170:173], v150
	ds_read_b128 v[174:177], v150 offset:1024
	ds_read_b128 v[180:183], v150 offset:2048
	ds_read_b128 v[184:187], v150 offset:3072
	s_add_i32 s64, s28, 2
	s_add_u32 s65, s26, 0x80
	s_addc_u32 s29, s27, 0
	s_cmp_eq_u32 s39, s28
	s_cselect_b32 s28, s0, s65
	s_cselect_b32 s29, s1, s29
	s_cselect_b32 s67, s25, s63
	s_cselect_b32 s66, s24, s62
	v_lshl_add_u64 v[144:145], s[26:27], 0, v[136:137]
	s_add_i32 m0, s30, 0xc000
	ds_read_b128 v[188:191], v151
	ds_read_b128 v[192:195], v151 offset:1024
	ds_read_b128 v[196:199], v151 offset:2048
	ds_read_b128 v[200:203], v151 offset:3072
	ds_read_b128 v[204:207], v151 offset:4096
	ds_read_b128 v[208:211], v151 offset:5120
	ds_read_b128 v[212:215], v151 offset:6144
	ds_read_b128 v[216:219], v151 offset:7168
	global_load_lds_dwordx4 v[144:145], off
	v_lshl_add_u64 v[144:145], s[26:27], 0, v[138:139]
	s_add_i32 m0, s30, 0xe000
	s_nop 0
	global_load_lds_dwordx4 v[144:145], off
	s_waitcnt vmcnt(14)
	s_waitcnt lgkmcnt(0)
	s_barrier
	s_setprio 1
	s_waitcnt lgkmcnt(0)
	v_mfma_f32_16x16x32_bf16 v[116:119], v[154:157], v[188:191], 0
	v_mfma_f32_16x16x32_bf16 v[112:115], v[162:165], v[188:191], 0
	v_mfma_f32_16x16x32_bf16 v[100:103], v[154:157], v[196:199], 0
	v_mfma_f32_16x16x32_bf16 v[96:99], v[162:165], v[196:199], 0
	v_mfma_f32_16x16x32_bf16 v[84:87], v[154:157], v[204:207], 0
	v_mfma_f32_16x16x32_bf16 v[80:83], v[162:165], v[204:207], 0
	v_mfma_f32_16x16x32_bf16 v[68:71], v[154:157], v[212:215], 0
	v_mfma_f32_16x16x32_bf16 v[64:67], v[162:165], v[212:215], 0
	v_mfma_f32_16x16x32_bf16 v[116:119], v[158:161], v[192:195], v[116:119]
	v_mfma_f32_16x16x32_bf16 v[112:115], v[166:169], v[192:195], v[112:115]
	v_mfma_f32_16x16x32_bf16 v[100:103], v[158:161], v[200:203], v[100:103]
	v_mfma_f32_16x16x32_bf16 v[96:99], v[166:169], v[200:203], v[96:99]
	v_mfma_f32_16x16x32_bf16 v[84:87], v[158:161], v[208:211], v[84:87]
	v_mfma_f32_16x16x32_bf16 v[80:83], v[166:169], v[208:211], v[80:83]
	v_mfma_f32_16x16x32_bf16 v[68:71], v[158:161], v[216:219], v[68:71]
	v_mfma_f32_16x16x32_bf16 v[64:67], v[166:169], v[216:219], v[64:67]
	s_setprio 0
	s_setprio 1
	v_mfma_f32_16x16x32_bf16 v[124:127], v[170:173], v[188:191], 0
	v_mfma_f32_16x16x32_bf16 v[120:123], v[180:183], v[188:191], 0
	v_mfma_f32_16x16x32_bf16 v[108:111], v[170:173], v[196:199], 0
	v_mfma_f32_16x16x32_bf16 v[104:107], v[180:183], v[196:199], 0
	v_mfma_f32_16x16x32_bf16 v[92:95], v[170:173], v[204:207], 0
	v_mfma_f32_16x16x32_bf16 v[88:91], v[180:183], v[204:207], 0
	v_mfma_f32_16x16x32_bf16 v[76:79], v[170:173], v[212:215], 0
	v_mfma_f32_16x16x32_bf16 v[72:75], v[180:183], v[212:215], 0
	v_mfma_f32_16x16x32_bf16 v[124:127], v[174:177], v[192:195], v[124:127]
	v_mfma_f32_16x16x32_bf16 v[120:123], v[184:187], v[192:195], v[120:123]
	v_mfma_f32_16x16x32_bf16 v[108:111], v[174:177], v[200:203], v[108:111]
	v_mfma_f32_16x16x32_bf16 v[104:107], v[184:187], v[200:203], v[104:107]
	v_mfma_f32_16x16x32_bf16 v[92:95], v[174:177], v[208:211], v[92:95]
	v_mfma_f32_16x16x32_bf16 v[88:91], v[184:187], v[208:211], v[88:91]
	v_mfma_f32_16x16x32_bf16 v[76:79], v[174:177], v[216:219], v[76:79]
	v_mfma_f32_16x16x32_bf16 v[72:75], v[184:187], v[216:219], v[72:75]
	s_setprio 0
	s_barrier
	s_add_i32 s65, s50, s16
	v_lshl_add_u64 v[144:145], s[66:67], 0, v[132:133]
	s_mov_b32 m0, s65
	ds_read_b128 v[188:191], v151 offset:16384
	ds_read_b128 v[192:195], v151 offset:17408
	ds_read_b128 v[196:199], v151 offset:18432
	ds_read_b128 v[200:203], v151 offset:19456
	ds_read_b128 v[204:207], v151 offset:20480
	ds_read_b128 v[208:211], v151 offset:21504
	ds_read_b128 v[212:215], v151 offset:22528
	ds_read_b128 v[216:219], v151 offset:23552
	global_load_lds_dwordx4 v[144:145], off
	s_add_i32 m0, s65, 0x2000
	v_lshl_add_u64 v[178:179], s[66:67], 0, v[128:129]
	s_add_u32 s66, s66, s8
	s_addc_u32 s67, s67, s9
	s_add_i32 s65, s51, s16
	global_load_lds_dwordx4 v[178:179], off
	v_lshl_add_u64 v[220:221], s[66:67], 0, v[132:133]
	s_mov_b32 m0, s65
	v_lshl_add_u64 v[222:223], s[66:67], 0, v[128:129]
	global_load_lds_dwordx4 v[220:221], off
	s_add_i32 m0, s65, 0x2000
	v_lshl_add_u64 v[224:225], s[28:29], 0, v[134:135]
	global_load_lds_dwordx4 v[222:223], off
	s_mov_b32 m0, s30
	v_lshl_add_u64 v[226:227], s[28:29], 0, v[130:131]
	global_load_lds_dwordx4 v[224:225], off
	s_mov_b32 m0, s31
	s_nop 0
	global_load_lds_dwordx4 v[226:227], off
	s_waitcnt vmcnt(20)
	s_waitcnt lgkmcnt(0)
	s_barrier
; #define PG8_STAGE(bufoff, gbase, voff) do { _Pragma("unroll") for (int _i = 0; _i < 2; ++_i) \
;         __builtin_amdgcn_global_load_lds((const unsigned*)((const char*)(gbase) + (voff)[_i]), (PG8_LAS unsigned*)(lds + (bufoff) + ldsw + _i * 8192), 16, 0, 0); } while (0)
; #define PG8_LDA(dst, b, h) do { _Pragma("unroll") for (int m = 0; m < 4; ++m) _Pragma("unroll") for (int k = 0; k < 2; ++k) dst[m][k] = *(const PG8_LAS bf16x8*)(lds + PG8_SA(b, h) + aoff + m * 2048 + k * 1024); } while (0)
; #define PG8_LDB(dst, b, h) do { _Pragma("unroll") for (int n = 0; n < 2; ++n) _Pragma("unroll") for (int k = 0; k < 2; ++k) dst[n][k] = *(const PG8_LAS bf16x8*)(lds + PG8_SB(b, h) + boff + n * 2048 + k * 1024); } while (0)
; #define PG8_MMA(ai, bj, At, Bt) do { __builtin_amdgcn_s_setprio(1); _Pragma("unroll") for (int m = 0; m < 4; ++m) _Pragma("unroll") for (int n = 0; n < 2; ++n) _Pragma("unroll") for (int k = 0; k < 2; ++k) \
;         acc[ai][bj][m][n] = __builtin_amdgcn_mfma_f32_16x16x32_bf16(Bt[n][k], At[m][k], acc[ai][bj][m][n], 0, 0, 0); __builtin_amdgcn_s_setprio(0); } while (0)
; #define PG8_WAIT_V(n) asm volatile("s_waitcnt vmcnt(" #n ")" ::: "memory")
; #define PG8_WAIT_L(n) asm volatile("s_waitcnt lgkmcnt(" #n ")" ::: "memory")
; #define PG8_BAR __builtin_amdgcn_s_barrier()
; #define PG8_SCHED __builtin_amdgcn_sched_barrier(0)
; template <class Epi, class Sched, bool ALIGN_EPI = false, bool SP2 = false>
; __device__ __forceinline__ void gemm_phase(PG8_LAS unsigned char* lds, const Gemm g, const Sched& S, const Epi& E) {
;     ...
;             PG8_WAIT_V(8); PG8_WAIT_L(0); PG8_BAR; PG8_MMA(1, 0, At, B0); PG8_MMA(1, 1, At, B1); PG8_BAR; PG8_SCHED;
;             PG8_LDB(B0, 1, 0); PG8_LDB(B1, 1, 1); PG8_SCHED; PG8_LDA(At, 1, 0); PG8_STAGE(PG8_SA(0, 1), a2 + hstep, voffA);
;             PG8_WAIT_V(8); PG8_WAIT_L(0); PG8_BAR; PG8_MMA(0, 0, At, B0); PG8_MMA(0, 1, At, B1); PG8_BAR; PG8_SCHED;
	s_setprio 1
	s_waitcnt lgkmcnt(0)
	v_mfma_f32_16x16x32_bf16 v[52:55], v[154:157], v[188:191], 0
	v_mfma_f32_16x16x32_bf16 v[48:51], v[162:165], v[188:191], 0
	v_mfma_f32_16x16x32_bf16 v[36:39], v[154:157], v[196:199], 0
	v_mfma_f32_16x16x32_bf16 v[32:35], v[162:165], v[196:199], 0
	v_mfma_f32_16x16x32_bf16 v[20:23], v[154:157], v[204:207], 0
	v_mfma_f32_16x16x32_bf16 v[16:19], v[162:165], v[204:207], 0
	v_mfma_f32_16x16x32_bf16 v[4:7], v[154:157], v[212:215], 0
	v_mfma_f32_16x16x32_bf16 v[0:3], v[162:165], v[212:215], 0
	v_mfma_f32_16x16x32_bf16 v[52:55], v[158:161], v[192:195], v[52:55]
	v_mfma_f32_16x16x32_bf16 v[48:51], v[166:169], v[192:195], v[48:51]
	v_mfma_f32_16x16x32_bf16 v[36:39], v[158:161], v[200:203], v[36:39]
	v_mfma_f32_16x16x32_bf16 v[32:35], v[166:169], v[200:203], v[32:35]
	v_mfma_f32_16x16x32_bf16 v[20:23], v[158:161], v[208:211], v[20:23]
	v_mfma_f32_16x16x32_bf16 v[16:19], v[166:169], v[208:211], v[16:19]
	v_mfma_f32_16x16x32_bf16 v[4:7], v[158:161], v[216:219], v[4:7]
	v_mfma_f32_16x16x32_bf16 v[0:3], v[166:169], v[216:219], v[0:3]
	s_setprio 0
	s_setprio 1
	v_mfma_f32_16x16x32_bf16 v[60:63], v[170:173], v[188:191], 0
	v_mfma_f32_16x16x32_bf16 v[56:59], v[180:183], v[188:191], 0
	v_mfma_f32_16x16x32_bf16 v[44:47], v[170:173], v[196:199], 0
	v_mfma_f32_16x16x32_bf16 v[40:43], v[180:183], v[196:199], 0
	v_mfma_f32_16x16x32_bf16 v[28:31], v[170:173], v[204:207], 0
	v_mfma_f32_16x16x32_bf16 v[24:27], v[180:183], v[204:207], 0
	v_mfma_f32_16x16x32_bf16 v[12:15], v[170:173], v[212:215], 0
	v_mfma_f32_16x16x32_bf16 v[8:11], v[180:183], v[212:215], 0
	v_mfma_f32_16x16x32_bf16 v[60:63], v[174:177], v[192:195], v[60:63]
	v_mfma_f32_16x16x32_bf16 v[56:59], v[184:187], v[192:195], v[56:59]
	v_mfma_f32_16x16x32_bf16 v[44:47], v[174:177], v[200:203], v[44:47]
	v_mfma_f32_16x16x32_bf16 v[40:43], v[184:187], v[200:203], v[40:43]
	v_mfma_f32_16x16x32_bf16 v[28:31], v[174:177], v[208:211], v[28:31]
	v_mfma_f32_16x16x32_bf16 v[24:27], v[184:187], v[208:211], v[24:27]
	v_mfma_f32_16x16x32_bf16 v[12:15], v[174:177], v[216:219], v[12:15]
	v_mfma_f32_16x16x32_bf16 v[8:11], v[184:187], v[216:219], v[8:11]
	s_setprio 0
	s_barrier
	s_add_i32 s65, 0, 0x18000
	v_add_u32_e32 v153, s65, v147
	s_add_i32 s66, 0, 0x1c000
	ds_read_b128 v[154:157], v153
	ds_read_b128 v[158:161], v153 offset:1024
	ds_read_b128 v[162:165], v153 offset:2048
	ds_read_b128 v[166:169], v153 offset:3072
	v_add_u32_e32 v153, s66, v147
	ds_read_b128 v[170:173], v153
	ds_read_b128 v[174:177], v153 offset:1024
	ds_read_b128 v[180:183], v153 offset:2048
	ds_read_b128 v[184:187], v153 offset:3072
	s_add_u32 s28, s28, s8
	s_addc_u32 s29, s29, s9
	s_mov_b32 m0, s33
	v_lshl_add_u64 v[228:229], s[28:29], 0, v[134:135]
	ds_read_b128 v[188:191], v151 offset:32768
	ds_read_b128 v[192:195], v151 offset:33792
	ds_read_b128 v[196:199], v151 offset:34816
	ds_read_b128 v[200:203], v151 offset:35840
	ds_read_b128 v[204:207], v151 offset:36864
	ds_read_b128 v[208:211], v151 offset:37888
	ds_read_b128 v[212:215], v151 offset:38912
	ds_read_b128 v[216:219], v151 offset:39936
	global_load_lds_dwordx4 v[228:229], off
	v_lshl_add_u64 v[228:229], s[28:29], 0, v[130:131]
	s_mov_b32 m0, s34
	s_nop 0
	global_load_lds_dwordx4 v[228:229], off
	s_waitcnt vmcnt(8)
	s_waitcnt lgkmcnt(0)
	s_barrier
	s_setprio 1
	s_waitcnt lgkmcnt(0)
	v_mfma_f32_16x16x32_bf16 v[116:119], v[154:157], v[188:191], v[116:119]
	v_mfma_f32_16x16x32_bf16 v[112:115], v[162:165], v[188:191], v[112:115]
	v_mfma_f32_16x16x32_bf16 v[100:103], v[154:157], v[196:199], v[100:103]
	v_mfma_f32_16x16x32_bf16 v[96:99], v[162:165], v[196:199], v[96:99]
	v_mfma_f32_16x16x32_bf16 v[84:87], v[154:157], v[204:207], v[84:87]
	v_mfma_f32_16x16x32_bf16 v[80:83], v[162:165], v[204:207], v[80:83]
	v_mfma_f32_16x16x32_bf16 v[68:71], v[154:157], v[212:215], v[68:71]
	v_mfma_f32_16x16x32_bf16 v[64:67], v[162:165], v[212:215], v[64:67]
	v_mfma_f32_16x16x32_bf16 v[116:119], v[158:161], v[192:195], v[116:119]
	v_mfma_f32_16x16x32_bf16 v[112:115], v[166:169], v[192:195], v[112:115]
	v_mfma_f32_16x16x32_bf16 v[100:103], v[158:161], v[200:203], v[100:103]
	v_mfma_f32_16x16x32_bf16 v[96:99], v[166:169], v[200:203], v[96:99]
	v_mfma_f32_16x16x32_bf16 v[84:87], v[158:161], v[208:211], v[84:87]
	v_mfma_f32_16x16x32_bf16 v[80:83], v[166:169], v[208:211], v[80:83]
	v_mfma_f32_16x16x32_bf16 v[68:71], v[158:161], v[216:219], v[68:71]
	v_mfma_f32_16x16x32_bf16 v[64:67], v[166:169], v[216:219], v[64:67]
	s_setprio 0
	s_setprio 1
	v_mfma_f32_16x16x32_bf16 v[124:127], v[170:173], v[188:191], v[124:127]
	v_mfma_f32_16x16x32_bf16 v[120:123], v[180:183], v[188:191], v[120:123]
	v_mfma_f32_16x16x32_bf16 v[108:111], v[170:173], v[196:199], v[108:111]
	v_mfma_f32_16x16x32_bf16 v[104:107], v[180:183], v[196:199], v[104:107]
	v_mfma_f32_16x16x32_bf16 v[92:95], v[170:173], v[204:207], v[92:95]
	v_mfma_f32_16x16x32_bf16 v[88:91], v[180:183], v[204:207], v[88:91]
	v_mfma_f32_16x16x32_bf16 v[76:79], v[170:173], v[212:215], v[76:79]
	v_mfma_f32_16x16x32_bf16 v[72:75], v[180:183], v[212:215], v[72:75]
	v_mfma_f32_16x16x32_bf16 v[124:127], v[174:177], v[192:195], v[124:127]
	v_mfma_f32_16x16x32_bf16 v[120:123], v[184:187], v[192:195], v[120:123]
	v_mfma_f32_16x16x32_bf16 v[108:111], v[174:177], v[200:203], v[108:111]
	v_mfma_f32_16x16x32_bf16 v[104:107], v[184:187], v[200:203], v[104:107]
	v_mfma_f32_16x16x32_bf16 v[92:95], v[174:177], v[208:211], v[92:95]
	v_mfma_f32_16x16x32_bf16 v[88:91], v[184:187], v[208:211], v[88:91]
	v_mfma_f32_16x16x32_bf16 v[76:79], v[174:177], v[216:219], v[76:79]
	v_mfma_f32_16x16x32_bf16 v[72:75], v[184:187], v[216:219], v[72:75]
	s_setprio 0
	s_barrier
; #define PG8_STAGE(bufoff, gbase, voff) do { _Pragma("unroll") for (int _i = 0; _i < 2; ++_i) \
;         __builtin_amdgcn_global_load_lds((const unsigned*)((const char*)(gbase) + (voff)[_i]), (PG8_LAS unsigned*)(lds + (bufoff) + ldsw + _i * 8192), 16, 0, 0); } while (0)
; #define PG8_LDA(dst, b, h) do { _Pragma("unroll") for (int m = 0; m < 4; ++m) _Pragma("unroll") for (int k = 0; k < 2; ++k) dst[m][k] = *(const PG8_LAS bf16x8*)(lds + PG8_SA(b, h) + aoff + m * 2048 + k * 1024); } while (0)
; #define PG8_MMA(ai, bj, At, Bt) do { __builtin_amdgcn_s_setprio(1); _Pragma("unroll") for (int m = 0; m < 4; ++m) _Pragma("unroll") for (int n = 0; n < 2; ++n) _Pragma("unroll") for (int k = 0; k < 2; ++k) \
;         acc[ai][bj][m][n] = __builtin_amdgcn_mfma_f32_16x16x32_bf16(Bt[n][k], At[m][k], acc[ai][bj][m][n], 0, 0, 0); __builtin_amdgcn_s_setprio(0); } while (0)
; #define PG8_WAIT_V(n) asm volatile("s_waitcnt vmcnt(" #n ")" ::: "memory")
; #define PG8_WAIT_L(n) asm volatile("s_waitcnt lgkmcnt(" #n ")" ::: "memory")
; #define PG8_BAR __builtin_amdgcn_s_barrier()
; #define PG8_SCHED __builtin_amdgcn_sched_barrier(0)
; template <class Epi, class Sched, bool ALIGN_EPI = false, bool SP2 = false>
; __device__ __forceinline__ void gemm_phase(PG8_LAS unsigned char* lds, const Gemm g, const Sched& S, const Epi& E) {
;     ...
;             PG8_LDA(At, 1, 1); PG8_STAGE(PG8_SB(1, 0), b3, voffB); PG8_STAGE(PG8_SB(1, 1), b3 + hstep, voffB); PG8_STAGE(PG8_SA(1, 0), a3, voffA);
;             PG8_WAIT_V(8); PG8_WAIT_L(0); PG8_BAR; PG8_MMA(1, 0, At, B0); PG8_MMA(1, 1, At, B1); PG8_BAR; PG8_SCHED;
	s_add_i32 s28, s65, s16
	v_lshl_add_u64 v[144:145], v[144:145], 0, s[14:15]
	s_mov_b32 m0, s28
	ds_read_b128 v[188:191], v151 offset:49152
	ds_read_b128 v[192:195], v151 offset:50176
	ds_read_b128 v[196:199], v151 offset:51200
	ds_read_b128 v[200:203], v151 offset:52224
	ds_read_b128 v[204:207], v151 offset:53248
	ds_read_b128 v[208:211], v151 offset:54272
	ds_read_b128 v[212:215], v151 offset:55296
	ds_read_b128 v[216:219], v151 offset:56320
	global_load_lds_dwordx4 v[144:145], off
	v_lshl_add_u64 v[144:145], v[178:179], 0, s[14:15]
	s_add_i32 m0, s28, 0x2000
	s_add_i32 s28, s66, s16
	global_load_lds_dwordx4 v[144:145], off
	v_lshl_add_u64 v[144:145], v[220:221], 0, s[14:15]
	s_mov_b32 m0, s28
	s_nop 0
	global_load_lds_dwordx4 v[144:145], off
	v_lshl_add_u64 v[144:145], v[222:223], 0, s[14:15]
	s_add_i32 m0, s28, 0x2000
	s_nop 0
	global_load_lds_dwordx4 v[144:145], off
	v_lshl_add_u64 v[144:145], v[224:225], 0, s[14:15]
	s_mov_b32 m0, s36
	s_nop 0
	global_load_lds_dwordx4 v[144:145], off
	v_lshl_add_u64 v[144:145], v[226:227], 0, s[14:15]
	s_mov_b32 m0, s37
	s_nop 0
	global_load_lds_dwordx4 v[144:145], off
	s_waitcnt vmcnt(8)
	s_waitcnt lgkmcnt(0)
	s_barrier
	s_setprio 1
	s_waitcnt lgkmcnt(0)
	v_mfma_f32_16x16x32_bf16 v[52:55], v[154:157], v[188:191], v[52:55]
	v_mfma_f32_16x16x32_bf16 v[48:51], v[162:165], v[188:191], v[48:51]
	v_mfma_f32_16x16x32_bf16 v[36:39], v[154:157], v[196:199], v[36:39]
	v_mfma_f32_16x16x32_bf16 v[32:35], v[162:165], v[196:199], v[32:35]
	v_mfma_f32_16x16x32_bf16 v[20:23], v[154:157], v[204:207], v[20:23]
	v_mfma_f32_16x16x32_bf16 v[16:19], v[162:165], v[204:207], v[16:19]
	v_mfma_f32_16x16x32_bf16 v[4:7], v[154:157], v[212:215], v[4:7]
	v_mfma_f32_16x16x32_bf16 v[0:3], v[162:165], v[212:215], v[0:3]
	v_mfma_f32_16x16x32_bf16 v[52:55], v[158:161], v[192:195], v[52:55]
	v_mfma_f32_16x16x32_bf16 v[48:51], v[166:169], v[192:195], v[48:51]
	v_mfma_f32_16x16x32_bf16 v[36:39], v[158:161], v[200:203], v[36:39]
	v_mfma_f32_16x16x32_bf16 v[32:35], v[166:169], v[200:203], v[32:35]
	v_mfma_f32_16x16x32_bf16 v[20:23], v[158:161], v[208:211], v[20:23]
	v_mfma_f32_16x16x32_bf16 v[16:19], v[166:169], v[208:211], v[16:19]
	v_mfma_f32_16x16x32_bf16 v[4:7], v[158:161], v[216:219], v[4:7]
	v_mfma_f32_16x16x32_bf16 v[0:3], v[166:169], v[216:219], v[0:3]
	s_setprio 0
	s_setprio 1
	v_mfma_f32_16x16x32_bf16 v[60:63], v[170:173], v[188:191], v[60:63]
	v_mfma_f32_16x16x32_bf16 v[56:59], v[180:183], v[188:191], v[56:59]
	v_mfma_f32_16x16x32_bf16 v[44:47], v[170:173], v[196:199], v[44:47]
	v_mfma_f32_16x16x32_bf16 v[40:43], v[180:183], v[196:199], v[40:43]
	v_mfma_f32_16x16x32_bf16 v[28:31], v[170:173], v[204:207], v[28:31]
	v_mfma_f32_16x16x32_bf16 v[24:27], v[180:183], v[204:207], v[24:27]
	v_mfma_f32_16x16x32_bf16 v[12:15], v[170:173], v[212:215], v[12:15]
	v_mfma_f32_16x16x32_bf16 v[8:11], v[180:183], v[212:215], v[8:11]
	v_mfma_f32_16x16x32_bf16 v[60:63], v[174:177], v[192:195], v[60:63]
	v_mfma_f32_16x16x32_bf16 v[56:59], v[184:187], v[192:195], v[56:59]
	v_mfma_f32_16x16x32_bf16 v[44:47], v[174:177], v[200:203], v[44:47]
	v_mfma_f32_16x16x32_bf16 v[40:43], v[184:187], v[200:203], v[40:43]
	v_mfma_f32_16x16x32_bf16 v[28:31], v[174:177], v[208:211], v[28:31]
	v_mfma_f32_16x16x32_bf16 v[24:27], v[184:187], v[208:211], v[24:27]
	v_mfma_f32_16x16x32_bf16 v[12:15], v[174:177], v[216:219], v[12:15]
	v_mfma_f32_16x16x32_bf16 v[8:11], v[184:187], v[216:219], v[8:11]
	s_setprio 0
	s_barrier
	s_add_u32 s26, s26, 0x100
	s_addc_u32 s27, s27, 0
	s_add_u32 s62, s62, 0x100
	s_addc_u32 s63, s63, 0
	s_cmp_ge_i32 s64, s38
	s_mov_b32 s28, s64
	s_cbranch_scc0 .LBB0_1317
	s_branch .Lpeel_x4

; #define PG8_STAGE(bufoff, gbase, voff) do { _Pragma("unroll") for (int _i = 0; _i < 2; ++_i) \
;         __builtin_amdgcn_global_load_lds((const unsigned*)((const char*)(gbase) + (voff)[_i]), (PG8_LAS unsigned*)(lds + (bufoff) + ldsw + _i * 8192), 16, 0, 0); } while (0)
; #define PG8_WAIT_V(n) asm volatile("s_waitcnt vmcnt(" #n ")" ::: "memory")
; #define PG8_BAR __builtin_amdgcn_s_barrier()
; template <class Epi, class Sched, bool ALIGN_EPI = false, bool SP2 = false>
; __device__ __forceinline__ void gemm_phase(PG8_LAS unsigned char* lds, const Gemm g, const Sched& S, const Epi& E) {
;     ...
;     for (int i = 0; i < 2; ++i) { int R, C; stage_rc(tid * 16 + i * 8192, R, C); const int Rb = Epi::PERM ? ((R & ~31) + perm32(R & 31)) : R;
;         voffA[i] = (unsigned)(R * K + C) * 2u; voffB[i] = (unsigned)(Rb * K + C) * 2u; }
;     const size_t kstep = (size_t)(BK * 2);
;     const size_t hstep = (size_t)HALF * K * 2;
;     const size_t tstep = 2 * hstep;
;     const unsigned ldsw = (unsigned)wid * 1024u;
;     const int aoff = lds_byte(wr * 64 + fr, fq * 8), boff = lds_byte(wc * 32 + fr, fq * 8);
;     ...
;         PG8_STAGE(PG8_SB(1, 0), cB + kstep, voffB); PG8_STAGE(PG8_SA(1, 0), cA + kstep, voffA); PG8_STAGE(PG8_SB(1, 1), cB + hstep + kstep, voffB);
;         PG8_WAIT_V(6); PG8_BAR;
.LBB0_2470:
	s_mov_b64 s[14:15], 0x80
	s_add_i32 m0, s30, 0x18000
	v_lshl_add_u64 v[8:9], v[8:9], 0, s[14:15]
	s_waitcnt vmcnt(2)
	s_barrier
	global_load_lds_dwordx4 v[8:9], off
	v_lshl_add_u64 v[4:5], v[4:5], 0, s[14:15]
	s_add_i32 m0, s30, 0x1a000
	s_add_i32 s36, s30, 0x8000
	global_load_lds_dwordx4 v[4:5], off
	v_lshl_add_u64 v[4:5], v[6:7], 0, s[14:15]
	s_mov_b32 m0, s36
	s_add_i32 s37, s30, 0xa000
	global_load_lds_dwordx4 v[4:5], off
	v_lshl_add_u64 v[4:5], v[10:11], 0, s[14:15]
	s_mov_b32 m0, s37
	v_lshl_add_u64 v[2:3], v[2:3], 0, s[14:15]
	global_load_lds_dwordx4 v[4:5], off
	s_add_i32 m0, s30, 0x1c000
	v_lshl_add_u64 v[0:1], v[0:1], 0, s[14:15]
	global_load_lds_dwordx4 v[2:3], off
	s_add_i32 m0, s30, 0x1e000
	s_lshr_b32 s1, s1, 26
	global_load_lds_dwordx4 v[0:1], off
	v_and_b32_e32 v0, 15, v254
	s_add_i32 s1, s0, s1
	v_lshlrev_b32_e32 v1, 1, v14
	v_lshlrev_b32_e32 v2, 2, v254
	s_ashr_i32 s38, s1, 6
	v_lshl_or_b32 v146, s21, 6, v0
	v_lshl_or_b32 v0, v0, 6, v1
	s_lshl_b32 s1, s21, 13
	v_and_b32_e32 v2, 32, v2
	v_bitop3_b32 v3, v0, s1, v2 bitop3:0xde
	s_lshl_b32 s1, s20, 5
	s_sext_i32_i16 s59, s2
	s_and_b32 s1, s1, 0x60
	v_lshlrev_b32_e32 v0, 6, v254
	s_movk_i32 s2, 0x3c0
	v_and_or_b32 v0, v0, s2, v1
	s_lshl_b32 s2, s1, 7
	v_bitop3_b32 v147, s2, v0, v2 bitop3:0xf6
	v_add_u32_e32 v0, v17, v16
	v_mul_lo_u32 v0, s0, v0
	v_lshlrev_b32_e32 v0, 1, v0
	v_add3_u32 v0, v12, v0, v13
	v_mov_b32_e32 v1, v133
	s_cmp_gt_i32 s0, 63
	v_lshl_add_u64 v[136:137], s[8:9], 0, v[0:1]
	v_add_u32_e32 v0, v15, v16
	s_cselect_b64 s[20:21], -1, 0
	s_add_i32 s39, s38, -2
	v_mul_lo_u32 v0, s0, v0
	s_waitcnt vmcnt(0)
	s_cmpk_lt_u32 s3, 0x100
	v_lshlrev_b32_e32 v0, 1, v0
	s_cselect_b64 s[22:23], -1, 0
	v_add3_u32 v0, v12, v0, v13
	s_add_i32 s44, 0, 0x10000
	s_add_i32 s45, 0, 0x14000
	s_ashr_i32 s40, s94, 31
	s_mov_b32 s41, s94
	v_or_b32_e32 v148, s1, v14
	v_lshl_add_u64 v[138:139], s[8:9], 0, v[0:1]
	v_mov_b64_e32 v[140:141], 0xb00
	v_mov_b64_e32 v[142:143], 0xaff
	v_add_u32_e32 v149, s44, v147
	v_add_u32_e32 v150, s45, v147
	v_add_u32_e32 v151, 0, v3
	v_mov_b32_e32 v152, 0x358637bd
	s_mov_b32 s50, 0x800000
	s_movk_i32 s51, 0x1600
	s_barrier
	s_branch .LBB0_2473

; #define PG8_STAGE(bufoff, gbase, voff) do { _Pragma("unroll") for (int _i = 0; _i < 2; ++_i) \
;         __builtin_amdgcn_global_load_lds((const unsigned*)((const char*)(gbase) + (voff)[_i]), (PG8_LAS unsigned*)(lds + (bufoff) + ldsw + _i * 8192), 16, 0, 0); } while (0)
; #define PG8_LDA(dst, b, h) do { _Pragma("unroll") for (int m = 0; m < 4; ++m) _Pragma("unroll") for (int k = 0; k < 2; ++k) dst[m][k] = *(const PG8_LAS bf16x8*)(lds + PG8_SA(b, h) + aoff + m * 2048 + k * 1024); } while (0)
; #define PG8_LDB(dst, b, h) do { _Pragma("unroll") for (int n = 0; n < 2; ++n) _Pragma("unroll") for (int k = 0; k < 2; ++k) dst[n][k] = *(const PG8_LAS bf16x8*)(lds + PG8_SB(b, h) + boff + n * 2048 + k * 1024); } while (0)
; #define PG8_MMA(ai, bj, At, Bt) do { __builtin_amdgcn_s_setprio(1); _Pragma("unroll") for (int m = 0; m < 4; ++m) _Pragma("unroll") for (int n = 0; n < 2; ++n) _Pragma("unroll") for (int k = 0; k < 2; ++k) \
;         acc[ai][bj][m][n] = __builtin_amdgcn_mfma_f32_16x16x32_bf16(Bt[n][k], At[m][k], acc[ai][bj][m][n], 0, 0, 0); __builtin_amdgcn_s_setprio(0); } while (0)
; #define PG8_WAIT_V(n) asm volatile("s_waitcnt vmcnt(" #n ")" ::: "memory")
; #define PG8_WAIT_L(n) asm volatile("s_waitcnt lgkmcnt(" #n ")" ::: "memory")
; #define PG8_BAR __builtin_amdgcn_s_barrier()
; #define PG8_SCHED __builtin_amdgcn_sched_barrier(0)
; template <class Epi, class Sched, bool ALIGN_EPI = false, bool SP2 = false>
; __device__ __forceinline__ void gemm_phase(PG8_LAS unsigned char* lds, const Gemm g, const Sched& S, const Epi& E) {
;     ...
;             PG8_LDB(B0, 0, 0); PG8_LDB(B1, 0, 1); PG8_SCHED; PG8_LDA(At, 0, 0); PG8_STAGE(PG8_SA(1, 1), a1 + hstep, voffA);
;             PG8_WAIT_V(8); PG8_WAIT_L(0); PG8_BAR; PG8_MMA(0, 0, At, B0); PG8_MMA(0, 1, At, B1); PG8_BAR; PG8_SCHED;
;             PG8_LDA(At, 0, 1); PG8_STAGE(PG8_SB(0, 0), b2, voffB); PG8_STAGE(PG8_SB(0, 1), b2 + hstep, voffB); PG8_STAGE(PG8_SA(0, 0), a2, voffA);
;             PG8_WAIT_V(8); PG8_WAIT_L(0); PG8_BAR; PG8_MMA(1, 0, At, B0); PG8_MMA(1, 1, At, B1); PG8_BAR; PG8_SCHED;
.LBB0_2479:
	s_andn2_b64 vcc, exec, s[20:21]
	s_waitcnt vmcnt(0)
	s_cbranch_vccnz .LBB0_2482
	s_add_u32 s26, s26, 0x80
	s_addc_u32 s27, s27, 0
	s_add_u32 s60, s28, 0x100
	s_addc_u32 s61, s29, 0
	s_mov_b32 s28, 0
	ds_read_b128 v[154:157], v149
	ds_read_b128 v[158:161], v149 offset:1024
	ds_read_b128 v[162:165], v149 offset:2048
	ds_read_b128 v[166:169], v149 offset:3072
	ds_read_b128 v[170:173], v150
	ds_read_b128 v[174:177], v150 offset:1024
	ds_read_b128 v[178:181], v150 offset:2048
	ds_read_b128 v[182:185], v150 offset:3072
	s_add_i32 s62, s28, 2
	s_add_u32 s63, s26, 0x80
	s_addc_u32 s29, s27, 0
	s_cmp_eq_u32 s39, s28
	s_cselect_b32 s28, s0, s63
	s_cselect_b32 s29, s1, s29
	s_cselect_b32 s65, s25, s61
	s_cselect_b32 s64, s24, s60
	v_lshl_add_u64 v[144:145], s[26:27], 0, v[136:137]
	s_add_i32 m0, s30, 0xc000
	ds_read_b128 v[186:189], v151
	ds_read_b128 v[190:193], v151 offset:1024
	ds_read_b128 v[194:197], v151 offset:2048
	ds_read_b128 v[198:201], v151 offset:3072
	ds_read_b128 v[202:205], v151 offset:4096
	ds_read_b128 v[206:209], v151 offset:5120
	ds_read_b128 v[210:213], v151 offset:6144
	ds_read_b128 v[214:217], v151 offset:7168
	global_load_lds_dwordx4 v[144:145], off
	v_lshl_add_u64 v[144:145], s[26:27], 0, v[138:139]
	s_add_i32 m0, s30, 0xe000
	s_nop 0
	global_load_lds_dwordx4 v[144:145], off
	s_waitcnt vmcnt(14)
	s_waitcnt lgkmcnt(0)
	s_barrier
	s_setprio 1
	s_waitcnt lgkmcnt(0)
	v_mfma_f32_16x16x32_bf16 v[116:119], v[154:157], v[186:189], 0
	v_mfma_f32_16x16x32_bf16 v[112:115], v[162:165], v[186:189], 0
	v_mfma_f32_16x16x32_bf16 v[100:103], v[154:157], v[194:197], 0
	v_mfma_f32_16x16x32_bf16 v[96:99], v[162:165], v[194:197], 0
	v_mfma_f32_16x16x32_bf16 v[84:87], v[154:157], v[202:205], 0
	v_mfma_f32_16x16x32_bf16 v[80:83], v[162:165], v[202:205], 0
	v_mfma_f32_16x16x32_bf16 v[68:71], v[154:157], v[210:213], 0
	v_mfma_f32_16x16x32_bf16 v[64:67], v[162:165], v[210:213], 0
	v_mfma_f32_16x16x32_bf16 v[116:119], v[158:161], v[190:193], v[116:119]
	v_mfma_f32_16x16x32_bf16 v[112:115], v[166:169], v[190:193], v[112:115]
	v_mfma_f32_16x16x32_bf16 v[100:103], v[158:161], v[198:201], v[100:103]
	v_mfma_f32_16x16x32_bf16 v[96:99], v[166:169], v[198:201], v[96:99]
	v_mfma_f32_16x16x32_bf16 v[84:87], v[158:161], v[206:209], v[84:87]
	v_mfma_f32_16x16x32_bf16 v[80:83], v[166:169], v[206:209], v[80:83]
	v_mfma_f32_16x16x32_bf16 v[68:71], v[158:161], v[214:217], v[68:71]
	v_mfma_f32_16x16x32_bf16 v[64:67], v[166:169], v[214:217], v[64:67]
	s_setprio 0
	s_setprio 1
	v_mfma_f32_16x16x32_bf16 v[124:127], v[170:173], v[186:189], 0
	v_mfma_f32_16x16x32_bf16 v[120:123], v[178:181], v[186:189], 0
	v_mfma_f32_16x16x32_bf16 v[108:111], v[170:173], v[194:197], 0
	v_mfma_f32_16x16x32_bf16 v[104:107], v[178:181], v[194:197], 0
	v_mfma_f32_16x16x32_bf16 v[92:95], v[170:173], v[202:205], 0
	v_mfma_f32_16x16x32_bf16 v[88:91], v[178:181], v[202:205], 0
	v_mfma_f32_16x16x32_bf16 v[76:79], v[170:173], v[210:213], 0
	v_mfma_f32_16x16x32_bf16 v[72:75], v[178:181], v[210:213], 0
	v_mfma_f32_16x16x32_bf16 v[124:127], v[174:177], v[190:193], v[124:127]
	v_mfma_f32_16x16x32_bf16 v[120:123], v[182:185], v[190:193], v[120:123]
	v_mfma_f32_16x16x32_bf16 v[108:111], v[174:177], v[198:201], v[108:111]
	v_mfma_f32_16x16x32_bf16 v[104:107], v[182:185], v[198:201], v[104:107]
	v_mfma_f32_16x16x32_bf16 v[92:95], v[174:177], v[206:209], v[92:95]
	v_mfma_f32_16x16x32_bf16 v[88:91], v[182:185], v[206:209], v[88:91]
	v_mfma_f32_16x16x32_bf16 v[76:79], v[174:177], v[214:217], v[76:79]
	v_mfma_f32_16x16x32_bf16 v[72:75], v[182:185], v[214:217], v[72:75]
	s_setprio 0
	s_barrier
	s_add_i32 s63, s44, s16
	v_lshl_add_u64 v[144:145], s[64:65], 0, v[132:133]
	s_mov_b32 m0, s63
	ds_read_b128 v[186:189], v151 offset:16384
	ds_read_b128 v[190:193], v151 offset:17408
	ds_read_b128 v[194:197], v151 offset:18432
	ds_read_b128 v[198:201], v151 offset:19456
	ds_read_b128 v[202:205], v151 offset:20480
	ds_read_b128 v[206:209], v151 offset:21504
	ds_read_b128 v[210:213], v151 offset:22528
	ds_read_b128 v[214:217], v151 offset:23552
	global_load_lds_dwordx4 v[144:145], off
	s_add_i32 m0, s63, 0x2000
	v_lshl_add_u64 v[218:219], s[64:65], 0, v[128:129]
	s_add_u32 s64, s64, s8
	s_addc_u32 s65, s65, s9
	s_add_i32 s63, s45, s16
	global_load_lds_dwordx4 v[218:219], off
	v_lshl_add_u64 v[220:221], s[64:65], 0, v[132:133]
	s_mov_b32 m0, s63
	v_lshl_add_u64 v[222:223], s[64:65], 0, v[128:129]
	global_load_lds_dwordx4 v[220:221], off
	s_add_i32 m0, s63, 0x2000
	v_lshl_add_u64 v[224:225], s[28:29], 0, v[134:135]
	global_load_lds_dwordx4 v[222:223], off
	s_mov_b32 m0, s30
	v_lshl_add_u64 v[226:227], s[28:29], 0, v[130:131]
	global_load_lds_dwordx4 v[224:225], off
	s_mov_b32 m0, s31
	s_nop 0
	global_load_lds_dwordx4 v[226:227], off
	s_waitcnt vmcnt(20)
	s_waitcnt lgkmcnt(0)
	s_barrier
; #define PG8_STAGE(bufoff, gbase, voff) do { _Pragma("unroll") for (int _i = 0; _i < 2; ++_i) \
;         __builtin_amdgcn_global_load_lds((const unsigned*)((const char*)(gbase) + (voff)[_i]), (PG8_LAS unsigned*)(lds + (bufoff) + ldsw + _i * 8192), 16, 0, 0); } while (0)
; #define PG8_LDA(dst, b, h) do { _Pragma("unroll") for (int m = 0; m < 4; ++m) _Pragma("unroll") for (int k = 0; k < 2; ++k) dst[m][k] = *(const PG8_LAS bf16x8*)(lds + PG8_SA(b, h) + aoff + m * 2048 + k * 1024); } while (0)
; #define PG8_LDB(dst, b, h) do { _Pragma("unroll") for (int n = 0; n < 2; ++n) _Pragma("unroll") for (int k = 0; k < 2; ++k) dst[n][k] = *(const PG8_LAS bf16x8*)(lds + PG8_SB(b, h) + boff + n * 2048 + k * 1024); } while (0)
; #define PG8_MMA(ai, bj, At, Bt) do { __builtin_amdgcn_s_setprio(1); _Pragma("unroll") for (int m = 0; m < 4; ++m) _Pragma("unroll") for (int n = 0; n < 2; ++n) _Pragma("unroll") for (int k = 0; k < 2; ++k) \
;         acc[ai][bj][m][n] = __builtin_amdgcn_mfma_f32_16x16x32_bf16(Bt[n][k], At[m][k], acc[ai][bj][m][n], 0, 0, 0); __builtin_amdgcn_s_setprio(0); } while (0)
; #define PG8_WAIT_V(n) asm volatile("s_waitcnt vmcnt(" #n ")" ::: "memory")
; #define PG8_WAIT_L(n) asm volatile("s_waitcnt lgkmcnt(" #n ")" ::: "memory")
; #define PG8_BAR __builtin_amdgcn_s_barrier()
; #define PG8_SCHED __builtin_amdgcn_sched_barrier(0)
; template <class Epi, class Sched, bool ALIGN_EPI = false, bool SP2 = false>
; __device__ __forceinline__ void gemm_phase(PG8_LAS unsigned char* lds, const Gemm g, const Sched& S, const Epi& E) {
;     ...
;             PG8_WAIT_V(8); PG8_WAIT_L(0); PG8_BAR; PG8_MMA(1, 0, At, B0); PG8_MMA(1, 1, At, B1); PG8_BAR; PG8_SCHED;
;             PG8_LDB(B0, 1, 0); PG8_LDB(B1, 1, 1); PG8_SCHED; PG8_LDA(At, 1, 0); PG8_STAGE(PG8_SA(0, 1), a2 + hstep, voffA);
;             PG8_WAIT_V(8); PG8_WAIT_L(0); PG8_BAR; PG8_MMA(0, 0, At, B0); PG8_MMA(0, 1, At, B1); PG8_BAR; PG8_SCHED;
	s_setprio 1
	s_waitcnt lgkmcnt(0)
	v_mfma_f32_16x16x32_bf16 v[52:55], v[154:157], v[186:189], 0
	v_mfma_f32_16x16x32_bf16 v[48:51], v[162:165], v[186:189], 0
	v_mfma_f32_16x16x32_bf16 v[36:39], v[154:157], v[194:197], 0
	v_mfma_f32_16x16x32_bf16 v[32:35], v[162:165], v[194:197], 0
	v_mfma_f32_16x16x32_bf16 v[20:23], v[154:157], v[202:205], 0
	v_mfma_f32_16x16x32_bf16 v[16:19], v[162:165], v[202:205], 0
	v_mfma_f32_16x16x32_bf16 v[4:7], v[154:157], v[210:213], 0
	v_mfma_f32_16x16x32_bf16 v[0:3], v[162:165], v[210:213], 0
	v_mfma_f32_16x16x32_bf16 v[52:55], v[158:161], v[190:193], v[52:55]
	v_mfma_f32_16x16x32_bf16 v[48:51], v[166:169], v[190:193], v[48:51]
	v_mfma_f32_16x16x32_bf16 v[36:39], v[158:161], v[198:201], v[36:39]
	v_mfma_f32_16x16x32_bf16 v[32:35], v[166:169], v[198:201], v[32:35]
	v_mfma_f32_16x16x32_bf16 v[20:23], v[158:161], v[206:209], v[20:23]
	v_mfma_f32_16x16x32_bf16 v[16:19], v[166:169], v[206:209], v[16:19]
	v_mfma_f32_16x16x32_bf16 v[4:7], v[158:161], v[214:217], v[4:7]
	v_mfma_f32_16x16x32_bf16 v[0:3], v[166:169], v[214:217], v[0:3]
	s_setprio 0
	s_setprio 1
	v_mfma_f32_16x16x32_bf16 v[60:63], v[170:173], v[186:189], 0
	v_mfma_f32_16x16x32_bf16 v[56:59], v[178:181], v[186:189], 0
	v_mfma_f32_16x16x32_bf16 v[44:47], v[170:173], v[194:197], 0
	v_mfma_f32_16x16x32_bf16 v[40:43], v[178:181], v[194:197], 0
	v_mfma_f32_16x16x32_bf16 v[28:31], v[170:173], v[202:205], 0
	v_mfma_f32_16x16x32_bf16 v[24:27], v[178:181], v[202:205], 0
	v_mfma_f32_16x16x32_bf16 v[12:15], v[170:173], v[210:213], 0
	v_mfma_f32_16x16x32_bf16 v[8:11], v[178:181], v[210:213], 0
	v_mfma_f32_16x16x32_bf16 v[60:63], v[174:177], v[190:193], v[60:63]
	v_mfma_f32_16x16x32_bf16 v[56:59], v[182:185], v[190:193], v[56:59]
	v_mfma_f32_16x16x32_bf16 v[44:47], v[174:177], v[198:201], v[44:47]
	v_mfma_f32_16x16x32_bf16 v[40:43], v[182:185], v[198:201], v[40:43]
	v_mfma_f32_16x16x32_bf16 v[28:31], v[174:177], v[206:209], v[28:31]
	v_mfma_f32_16x16x32_bf16 v[24:27], v[182:185], v[206:209], v[24:27]
	v_mfma_f32_16x16x32_bf16 v[12:15], v[174:177], v[214:217], v[12:15]
	v_mfma_f32_16x16x32_bf16 v[8:11], v[182:185], v[214:217], v[8:11]
	s_setprio 0
	s_barrier
	s_add_i32 s63, 0, 0x18000
	v_add_u32_e32 v153, s63, v147
	s_add_i32 s64, 0, 0x1c000
	ds_read_b128 v[154:157], v153
	ds_read_b128 v[158:161], v153 offset:1024
	ds_read_b128 v[162:165], v153 offset:2048
	ds_read_b128 v[166:169], v153 offset:3072
	v_add_u32_e32 v153, s64, v147
	ds_read_b128 v[170:173], v153
	ds_read_b128 v[174:177], v153 offset:1024
	ds_read_b128 v[178:181], v153 offset:2048
	ds_read_b128 v[182:185], v153 offset:3072
	s_add_u32 s28, s28, s8
	s_addc_u32 s29, s29, s9
	s_mov_b32 m0, s33
	v_lshl_add_u64 v[228:229], s[28:29], 0, v[134:135]
	ds_read_b128 v[186:189], v151 offset:32768
	ds_read_b128 v[190:193], v151 offset:33792
	ds_read_b128 v[194:197], v151 offset:34816
	ds_read_b128 v[198:201], v151 offset:35840
	ds_read_b128 v[202:205], v151 offset:36864
	ds_read_b128 v[206:209], v151 offset:37888
	ds_read_b128 v[210:213], v151 offset:38912
	ds_read_b128 v[214:217], v151 offset:39936
	global_load_lds_dwordx4 v[228:229], off
	v_lshl_add_u64 v[228:229], s[28:29], 0, v[130:131]
	s_mov_b32 m0, s34
	s_nop 0
	global_load_lds_dwordx4 v[228:229], off
	s_waitcnt vmcnt(8)
	s_waitcnt lgkmcnt(0)
	s_barrier
	s_setprio 1
	s_waitcnt lgkmcnt(0)
	v_mfma_f32_16x16x32_bf16 v[116:119], v[154:157], v[186:189], v[116:119]
	v_mfma_f32_16x16x32_bf16 v[112:115], v[162:165], v[186:189], v[112:115]
	v_mfma_f32_16x16x32_bf16 v[100:103], v[154:157], v[194:197], v[100:103]
	v_mfma_f32_16x16x32_bf16 v[96:99], v[162:165], v[194:197], v[96:99]
	v_mfma_f32_16x16x32_bf16 v[84:87], v[154:157], v[202:205], v[84:87]
	v_mfma_f32_16x16x32_bf16 v[80:83], v[162:165], v[202:205], v[80:83]
	v_mfma_f32_16x16x32_bf16 v[68:71], v[154:157], v[210:213], v[68:71]
	v_mfma_f32_16x16x32_bf16 v[64:67], v[162:165], v[210:213], v[64:67]
	v_mfma_f32_16x16x32_bf16 v[116:119], v[158:161], v[190:193], v[116:119]
	v_mfma_f32_16x16x32_bf16 v[112:115], v[166:169], v[190:193], v[112:115]
	v_mfma_f32_16x16x32_bf16 v[100:103], v[158:161], v[198:201], v[100:103]
	v_mfma_f32_16x16x32_bf16 v[96:99], v[166:169], v[198:201], v[96:99]
	v_mfma_f32_16x16x32_bf16 v[84:87], v[158:161], v[206:209], v[84:87]
	v_mfma_f32_16x16x32_bf16 v[80:83], v[166:169], v[206:209], v[80:83]
	v_mfma_f32_16x16x32_bf16 v[68:71], v[158:161], v[214:217], v[68:71]
	v_mfma_f32_16x16x32_bf16 v[64:67], v[166:169], v[214:217], v[64:67]
	s_setprio 0
	s_setprio 1
	v_mfma_f32_16x16x32_bf16 v[124:127], v[170:173], v[186:189], v[124:127]
	v_mfma_f32_16x16x32_bf16 v[120:123], v[178:181], v[186:189], v[120:123]
	v_mfma_f32_16x16x32_bf16 v[108:111], v[170:173], v[194:197], v[108:111]
	v_mfma_f32_16x16x32_bf16 v[104:107], v[178:181], v[194:197], v[104:107]
	v_mfma_f32_16x16x32_bf16 v[92:95], v[170:173], v[202:205], v[92:95]
	v_mfma_f32_16x16x32_bf16 v[88:91], v[178:181], v[202:205], v[88:91]
	v_mfma_f32_16x16x32_bf16 v[76:79], v[170:173], v[210:213], v[76:79]
	v_mfma_f32_16x16x32_bf16 v[72:75], v[178:181], v[210:213], v[72:75]
	v_mfma_f32_16x16x32_bf16 v[124:127], v[174:177], v[190:193], v[124:127]
	v_mfma_f32_16x16x32_bf16 v[120:123], v[182:185], v[190:193], v[120:123]
	v_mfma_f32_16x16x32_bf16 v[108:111], v[174:177], v[198:201], v[108:111]
	v_mfma_f32_16x16x32_bf16 v[104:107], v[182:185], v[198:201], v[104:107]
	v_mfma_f32_16x16x32_bf16 v[92:95], v[174:177], v[206:209], v[92:95]
	v_mfma_f32_16x16x32_bf16 v[88:91], v[182:185], v[206:209], v[88:91]
	v_mfma_f32_16x16x32_bf16 v[76:79], v[174:177], v[214:217], v[76:79]
	v_mfma_f32_16x16x32_bf16 v[72:75], v[182:185], v[214:217], v[72:75]
	s_setprio 0
	s_barrier
; #define PG8_STAGE(bufoff, gbase, voff) do { _Pragma("unroll") for (int _i = 0; _i < 2; ++_i) \
;         __builtin_amdgcn_global_load_lds((const unsigned*)((const char*)(gbase) + (voff)[_i]), (PG8_LAS unsigned*)(lds + (bufoff) + ldsw + _i * 8192), 16, 0, 0); } while (0)
; #define PG8_LDA(dst, b, h) do { _Pragma("unroll") for (int m = 0; m < 4; ++m) _Pragma("unroll") for (int k = 0; k < 2; ++k) dst[m][k] = *(const PG8_LAS bf16x8*)(lds + PG8_SA(b, h) + aoff + m * 2048 + k * 1024); } while (0)
; #define PG8_MMA(ai, bj, At, Bt) do { __builtin_amdgcn_s_setprio(1); _Pragma("unroll") for (int m = 0; m < 4; ++m) _Pragma("unroll") for (int n = 0; n < 2; ++n) _Pragma("unroll") for (int k = 0; k < 2; ++k) \
;         acc[ai][bj][m][n] = __builtin_amdgcn_mfma_f32_16x16x32_bf16(Bt[n][k], At[m][k], acc[ai][bj][m][n], 0, 0, 0); __builtin_amdgcn_s_setprio(0); } while (0)
; #define PG8_WAIT_V(n) asm volatile("s_waitcnt vmcnt(" #n ")" ::: "memory")
; #define PG8_WAIT_L(n) asm volatile("s_waitcnt lgkmcnt(" #n ")" ::: "memory")
; #define PG8_BAR __builtin_amdgcn_s_barrier()
; #define PG8_SCHED __builtin_amdgcn_sched_barrier(0)
; template <class Epi, class Sched, bool ALIGN_EPI = false, bool SP2 = false>
; __device__ __forceinline__ void gemm_phase(PG8_LAS unsigned char* lds, const Gemm g, const Sched& S, const Epi& E) {
;     ...
;             PG8_LDA(At, 1, 1); PG8_STAGE(PG8_SB(1, 0), b3, voffB); PG8_STAGE(PG8_SB(1, 1), b3 + hstep, voffB); PG8_STAGE(PG8_SA(1, 0), a3, voffA);
;             PG8_WAIT_V(8); PG8_WAIT_L(0); PG8_BAR; PG8_MMA(1, 0, At, B0); PG8_MMA(1, 1, At, B1); PG8_BAR; PG8_SCHED;
	s_add_i32 s28, s63, s16
	v_lshl_add_u64 v[144:145], v[144:145], 0, s[14:15]
	s_mov_b32 m0, s28
	ds_read_b128 v[186:189], v151 offset:49152
	ds_read_b128 v[190:193], v151 offset:50176
	ds_read_b128 v[194:197], v151 offset:51200
	ds_read_b128 v[198:201], v151 offset:52224
	ds_read_b128 v[202:205], v151 offset:53248
	ds_read_b128 v[206:209], v151 offset:54272
	ds_read_b128 v[210:213], v151 offset:55296
	ds_read_b128 v[214:217], v151 offset:56320
	global_load_lds_dwordx4 v[144:145], off
	v_lshl_add_u64 v[144:145], v[218:219], 0, s[14:15]
	s_add_i32 m0, s28, 0x2000
	s_add_i32 s28, s64, s16
	global_load_lds_dwordx4 v[144:145], off
	v_lshl_add_u64 v[144:145], v[220:221], 0, s[14:15]
	s_mov_b32 m0, s28
	s_nop 0
	global_load_lds_dwordx4 v[144:145], off
	v_lshl_add_u64 v[144:145], v[222:223], 0, s[14:15]
	s_add_i32 m0, s28, 0x2000
	s_nop 0
	global_load_lds_dwordx4 v[144:145], off
	v_lshl_add_u64 v[144:145], v[224:225], 0, s[14:15]
	s_mov_b32 m0, s36
	s_nop 0
	global_load_lds_dwordx4 v[144:145], off
	v_lshl_add_u64 v[144:145], v[226:227], 0, s[14:15]
	s_mov_b32 m0, s37
	s_nop 0
	global_load_lds_dwordx4 v[144:145], off
	s_waitcnt vmcnt(8)
	s_waitcnt lgkmcnt(0)
	s_barrier
	s_setprio 1
	s_waitcnt lgkmcnt(0)
	v_mfma_f32_16x16x32_bf16 v[52:55], v[154:157], v[186:189], v[52:55]
	v_mfma_f32_16x16x32_bf16 v[48:51], v[162:165], v[186:189], v[48:51]
	v_mfma_f32_16x16x32_bf16 v[36:39], v[154:157], v[194:197], v[36:39]
	v_mfma_f32_16x16x32_bf16 v[32:35], v[162:165], v[194:197], v[32:35]
	v_mfma_f32_16x16x32_bf16 v[20:23], v[154:157], v[202:205], v[20:23]
	v_mfma_f32_16x16x32_bf16 v[16:19], v[162:165], v[202:205], v[16:19]
	v_mfma_f32_16x16x32_bf16 v[4:7], v[154:157], v[210:213], v[4:7]
	v_mfma_f32_16x16x32_bf16 v[0:3], v[162:165], v[210:213], v[0:3]
	v_mfma_f32_16x16x32_bf16 v[52:55], v[158:161], v[190:193], v[52:55]
	v_mfma_f32_16x16x32_bf16 v[48:51], v[166:169], v[190:193], v[48:51]
	v_mfma_f32_16x16x32_bf16 v[36:39], v[158:161], v[198:201], v[36:39]
	v_mfma_f32_16x16x32_bf16 v[32:35], v[166:169], v[198:201], v[32:35]
	v_mfma_f32_16x16x32_bf16 v[20:23], v[158:161], v[206:209], v[20:23]
	v_mfma_f32_16x16x32_bf16 v[16:19], v[166:169], v[206:209], v[16:19]
	v_mfma_f32_16x16x32_bf16 v[4:7], v[158:161], v[214:217], v[4:7]
	v_mfma_f32_16x16x32_bf16 v[0:3], v[166:169], v[214:217], v[0:3]
	s_setprio 0
	s_setprio 1
	v_mfma_f32_16x16x32_bf16 v[60:63], v[170:173], v[186:189], v[60:63]
	v_mfma_f32_16x16x32_bf16 v[56:59], v[178:181], v[186:189], v[56:59]
	v_mfma_f32_16x16x32_bf16 v[44:47], v[170:173], v[194:197], v[44:47]
	v_mfma_f32_16x16x32_bf16 v[40:43], v[178:181], v[194:197], v[40:43]
	v_mfma_f32_16x16x32_bf16 v[28:31], v[170:173], v[202:205], v[28:31]
	v_mfma_f32_16x16x32_bf16 v[24:27], v[178:181], v[202:205], v[24:27]
	v_mfma_f32_16x16x32_bf16 v[12:15], v[170:173], v[210:213], v[12:15]
	v_mfma_f32_16x16x32_bf16 v[8:11], v[178:181], v[210:213], v[8:11]
	v_mfma_f32_16x16x32_bf16 v[60:63], v[174:177], v[190:193], v[60:63]
	v_mfma_f32_16x16x32_bf16 v[56:59], v[182:185], v[190:193], v[56:59]
	v_mfma_f32_16x16x32_bf16 v[44:47], v[174:177], v[198:201], v[44:47]
	v_mfma_f32_16x16x32_bf16 v[40:43], v[182:185], v[198:201], v[40:43]
	v_mfma_f32_16x16x32_bf16 v[28:31], v[174:177], v[206:209], v[28:31]
	v_mfma_f32_16x16x32_bf16 v[24:27], v[182:185], v[206:209], v[24:27]
	v_mfma_f32_16x16x32_bf16 v[12:15], v[174:177], v[214:217], v[12:15]
	v_mfma_f32_16x16x32_bf16 v[8:11], v[182:185], v[214:217], v[8:11]
	s_setprio 0
	s_barrier
	s_add_u32 s26, s26, 0x100
	s_addc_u32 s27, s27, 0
	s_add_u32 s60, s60, 0x100
	s_addc_u32 s61, s61, 0
	s_cmp_ge_i32 s62, s38
	s_mov_b32 s28, s62
	s_cbranch_scc0 .LBB0_2481
	s_branch .Lpeel_x12
